# first K-loop iteration after an epilogue: first two DMA waits relaxed so the loop does not wait for the epilogue's store acks (all five GEMM loops)
# baseline (speedup 1.0000x reference)
; #define PG8_STAGE(bufoff, gbase, voff) do { _Pragma("unroll") for (int _i = 0; _i < 2; ++_i) \
;         __builtin_amdgcn_global_load_lds((const unsigned*)((const char*)(gbase) + (voff)[_i]), (PG8_LAS unsigned*)(lds + (bufoff) + ldsw + _i * 8192), 16, 0, 0); } while (0)
; #define PG8_WAIT_V(n) asm volatile("s_waitcnt vmcnt(" #n ")" ::: "memory")
; #define PG8_BAR __builtin_amdgcn_s_barrier()
; template <class Epi, class Sched, bool ALIGN_EPI = false, bool SP2 = false>
; __device__ __forceinline__ void gemm_phase(PG8_LAS unsigned char* lds, const Gemm g, const Sched& S, const Epi& E) {
;     ...
;     for (int i = 0; i < 2; ++i) { int R, C; stage_rc(tid * 16 + i * 8192, R, C); const int Rb = Epi::PERM ? ((R & ~31) + perm32(R & 31)) : R;
;         voffA[i] = (unsigned)(R * K + C) * 2u; voffB[i] = (unsigned)(Rb * K + C) * 2u; }
;     const size_t kstep = (size_t)(BK * 2);
;     const size_t hstep = (size_t)HALF * K * 2;
;     const size_t tstep = 2 * hstep;
;     const unsigned ldsw = (unsigned)wid * 1024u;
;     const int aoff = lds_byte(wr * 64 + fr, fq * 8), boff = lds_byte(wc * 32 + fr, fq * 8);
;     ...
;         PG8_WAIT_V(2); PG8_BAR;
;         PG8_STAGE(PG8_SB(1, 0), cB + kstep, voffB); PG8_STAGE(PG8_SA(1, 0), cA + kstep, voffA); PG8_STAGE(PG8_SB(1, 1), cB + hstep + kstep, voffB);
;         PG8_WAIT_V(6); PG8_BAR;
.LBB0_112:
	s_lshl_b32 s3, s3, 5
	s_and_b32 s90, s3, 0x60
	s_add_i32 m0, s71, 0x18000
	v_lshl_add_u64 v[6:7], v[6:7], 0, s[14:15]
	s_lshl_b32 s22, s2, 13
	s_lshl_b32 s3, s90, 7
	s_waitcnt vmcnt(2)
	s_barrier
	global_load_lds_dwordx4 v[6:7], off
	v_lshl_add_u64 v[4:5], v[4:5], 0, s[14:15]
	s_add_i32 m0, s71, 0x1a000
	s_add_i32 s91, s71, 0x8000
	s_add_i32 s92, s71, 0xa000
	global_load_lds_dwordx4 v[4:5], off
	v_lshl_add_u64 v[0:1], v[0:1], 0, s[14:15]
	s_mov_b32 m0, s91
	s_add_u32 s24, s46, 0x30080
	global_load_lds_dwordx4 v[0:1], off
	v_lshl_add_u64 v[0:1], v[2:3], 0, s[14:15]
	s_mov_b32 m0, s92
	s_addc_u32 s25, s47, 0
	global_load_lds_dwordx4 v[0:1], off
	s_add_i32 m0, s71, 0x1c000
	v_lshl_add_u64 v[0:1], s[24:25], 0, v[128:129]
	global_load_lds_dwordx4 v[0:1], off
	v_lshl_add_u64 v[0:1], s[24:25], 0, v[130:131]
	s_add_i32 m0, s71, 0x1e000
	v_lshlrev_b32_e32 v3, 2, v8
	global_load_lds_dwordx4 v[0:1], off
	v_bfe_u32 v1, v8, 4, 2
	v_and_b32_e32 v0, 15, v8
	v_lshlrev_b32_e32 v2, 4, v1
	v_lshl_or_b32 v2, v0, 6, v2
	v_and_b32_e32 v3, 32, v3
	v_bitop3_b32 v4, v2, s22, v3 bitop3:0xde
	s_movk_i32 s22, 0x300
	v_lshl_or_b32 v141, s2, 6, v0
	s_cmpk_lt_u32 s12, 0x100
	v_lshlrev_b32_e32 v140, 2, v1
	v_or_b32_e32 v151, 0x1000, v0
	v_or_b32_e32 v152, 0x1010, v0
	v_lshrrev_b32_e32 v1, 1, v9
	v_mul_lo_u32 v0, v11, s22
	s_movk_i32 s12, 0x3000
	v_mad_u64_u32 v[0:1], s[24:25], v1, s12, v[0:1]
	v_or_b32_e32 v0, v0, v10
	v_add_lshl_u32 v132, v0, v12, 1
	v_lshrrev_b32_e32 v1, 1, v13
	v_mul_lo_u32 v0, v15, s22
	v_mad_u64_u32 v[0:1], s[24:25], v1, s12, v[0:1]
	s_waitcnt vmcnt(0)
	s_mov_b64 s[40:41], 0x30080
	v_or_b32_e32 v0, v0, v14
	v_lshl_add_u64 v[142:143], v[132:133], 0, s[40:41]
	v_add_lshl_u32 v132, v0, v16, 1
	v_bitop3_b32 v150, v2, s3, v3 bitop3:0xde
	s_cselect_b64 s[2:3], -1, 0
	s_ashr_i32 s93, s83, 31
	s_ashr_i32 s94, s84, 31
	v_lshl_add_u64 v[144:145], v[132:133], 0, s[40:41]
	s_mov_b32 s95, 0
	v_add_u32_e32 v153, 0, v4
	v_lshlrev_b32_e32 v132, 1, v140
	s_barrier
	s_branch .LBB0_115

; #define PG8_STAGE(bufoff, gbase, voff) do { _Pragma("unroll") for (int _i = 0; _i < 2; ++_i) \
;         __builtin_amdgcn_global_load_lds((const unsigned*)((const char*)(gbase) + (voff)[_i]), (PG8_LAS unsigned*)(lds + (bufoff) + ldsw + _i * 8192), 16, 0, 0); } while (0)
; #define PG8_LDA(dst, b, h) do { _Pragma("unroll") for (int m = 0; m < 4; ++m) _Pragma("unroll") for (int k = 0; k < 2; ++k) dst[m][k] = *(const PG8_LAS bf16x8*)(lds + PG8_SA(b, h) + aoff + m * 2048 + k * 1024); } while (0)
; #define PG8_LDB(dst, b, h) do { _Pragma("unroll") for (int n = 0; n < 2; ++n) _Pragma("unroll") for (int k = 0; k < 2; ++k) dst[n][k] = *(const PG8_LAS bf16x8*)(lds + PG8_SB(b, h) + boff + n * 2048 + k * 1024); } while (0)
; #define PG8_WAIT_V(n) asm volatile("s_waitcnt vmcnt(" #n ")" ::: "memory")
; #define PG8_WAIT_L(n) asm volatile("s_waitcnt lgkmcnt(" #n ")" ::: "memory")
; #define PG8_BAR __builtin_amdgcn_s_barrier()
; #define PG8_SCHED __builtin_amdgcn_sched_barrier(0)
; template <class Epi, class Sched, bool ALIGN_EPI = false, bool SP2 = false>
; __device__ __forceinline__ void gemm_phase(PG8_LAS unsigned char* lds, const Gemm g, const Sched& S, const Epi& E) {
;     ...
;         const char* nA = has_next ? (const char*)g.A + (size_t)nxt.pm * tstep : cA; const char* nB = has_next ? (const char*)g.Bt + (size_t)nxt.pn * tstep : cB;
;         for (int t = 0; t < nt; t += 2) {
;             const bool last = (t == nt - 2);
;             const char* a1 = cA + (size_t)(t + 1) * kstep;
;             const char* a2 = last ? nA : cA + (size_t)(t + 2) * kstep; const char* b2 = last ? nB : cB + (size_t)(t + 2) * kstep;
;             const char* a3 = a2 + kstep; const char* b3 = b2 + kstep;
;             if (last && has_next) S.a_ready(nxt);
;             if constexpr (SP2) {
;             PG8_LDB(B0, 0, 0); PG8_LDB(B1, 0, 1); PG8_SCHED; PG8_LDA(At, 0, 0); PG8_STAGE(PG8_SA(1, 1), a1 + hstep, voffA);
;             PG8_WAIT_V(8); PG8_WAIT_L(0); PG8_BAR; PG8_MMA(0, 0, At, B0); PG8_MMA(0, 1, At, B1); PG8_BAR; PG8_SCHED;
;             PG8_LDA(At, 0, 1); PG8_STAGE(PG8_SB(0, 0), b2, voffB); PG8_STAGE(PG8_SB(0, 1), b2 + hstep, voffB); PG8_STAGE(PG8_SA(0, 0), a2, voffA);
;             PG8_WAIT_V(8); PG8_WAIT_L(0); PG8_BAR; PG8_MMA(1, 0, At, B0); PG8_MMA(1, 1, At, B1); PG8_BAR; PG8_SCHED;
.LBB0_121:
	s_add_u32 s22, s46, 0x100
	s_addc_u32 s33, s47, 0
	s_mov_b32 s50, -2
	s_add_u32 s42, s44, 0x100
	s_addc_u32 s43, s45, 0
	s_add_i32 s24, 0, 0x10000
	s_cmp_eq_u32 s50, 8
	s_cselect_b32 s69, s65, s43
	s_cselect_b32 s68, s64, s42
	s_cselect_b32 s47, s67, s33
	s_cselect_b32 s46, s66, s22
	s_add_i32 s51, 0, 0x14000
	v_add_u32_e32 v162, s24, v150
	v_add_u32_e32 v170, s51, v150
	ds_read_b128 v[146:149], v162
	ds_read_b128 v[154:157], v162 offset:1024
	ds_read_b128 v[158:161], v162 offset:2048
	ds_read_b128 v[162:165], v162 offset:3072
	ds_read_b128 v[166:169], v170
	ds_read_b128 v[192:195], v170 offset:1024
	ds_read_b128 v[196:199], v170 offset:2048
	ds_read_b128 v[200:203], v170 offset:3072
	v_lshl_add_u64 v[170:171], s[44:45], 0, v[142:143]
	s_add_i32 m0, s71, 0xc000
	ds_read_b128 v[204:207], v153
	ds_read_b128 v[208:211], v153 offset:1024
	ds_read_b128 v[212:215], v153 offset:2048
	ds_read_b128 v[216:219], v153 offset:3072
	ds_read_b128 v[220:223], v153 offset:4096
	ds_read_b128 v[224:227], v153 offset:5120
	ds_read_b128 v[228:231], v153 offset:6144
	ds_read_b128 v[232:235], v153 offset:7168
	global_load_lds_dwordx4 v[170:171], off
	v_lshl_add_u64 v[170:171], s[44:45], 0, v[144:145]
	s_add_i32 m0, s71, 0xe000
	s_nop 0
	global_load_lds_dwordx4 v[170:171], off
	s_waitcnt vmcnt(36)
	s_waitcnt lgkmcnt(0)
	s_barrier
	s_setprio 1
	s_waitcnt lgkmcnt(0)
	v_mfma_f32_16x16x32_bf16 v[124:127], v[146:149], v[204:207], 0
	v_mfma_f32_16x16x32_bf16 v[120:123], v[158:161], v[204:207], 0
	v_mfma_f32_16x16x32_bf16 v[108:111], v[146:149], v[212:215], 0
	v_mfma_f32_16x16x32_bf16 v[104:107], v[158:161], v[212:215], 0
	v_mfma_f32_16x16x32_bf16 v[92:95], v[146:149], v[220:223], 0
	v_mfma_f32_16x16x32_bf16 v[88:91], v[158:161], v[220:223], 0
	v_mfma_f32_16x16x32_bf16 v[76:79], v[146:149], v[228:231], 0
	v_mfma_f32_16x16x32_bf16 v[72:75], v[158:161], v[228:231], 0
	v_mfma_f32_16x16x32_bf16 v[124:127], v[154:157], v[208:211], v[124:127]
	v_mfma_f32_16x16x32_bf16 v[120:123], v[162:165], v[208:211], v[120:123]
	v_mfma_f32_16x16x32_bf16 v[108:111], v[154:157], v[216:219], v[108:111]
	v_mfma_f32_16x16x32_bf16 v[104:107], v[162:165], v[216:219], v[104:107]
	v_mfma_f32_16x16x32_bf16 v[92:95], v[154:157], v[224:227], v[92:95]
	v_mfma_f32_16x16x32_bf16 v[88:91], v[162:165], v[224:227], v[88:91]
	v_mfma_f32_16x16x32_bf16 v[76:79], v[154:157], v[232:235], v[76:79]
	v_mfma_f32_16x16x32_bf16 v[72:75], v[162:165], v[232:235], v[72:75]
	s_setprio 0
	s_setprio 1
	v_mfma_f32_16x16x32_bf16 v[116:119], v[166:169], v[204:207], 0
	v_mfma_f32_16x16x32_bf16 v[112:115], v[196:199], v[204:207], 0
	v_mfma_f32_16x16x32_bf16 v[100:103], v[166:169], v[212:215], 0
	v_mfma_f32_16x16x32_bf16 v[96:99], v[196:199], v[212:215], 0
	v_mfma_f32_16x16x32_bf16 v[84:87], v[166:169], v[220:223], 0
	v_mfma_f32_16x16x32_bf16 v[80:83], v[196:199], v[220:223], 0
	v_mfma_f32_16x16x32_bf16 v[68:71], v[166:169], v[228:231], 0
	v_mfma_f32_16x16x32_bf16 v[64:67], v[196:199], v[228:231], 0
	v_mfma_f32_16x16x32_bf16 v[116:119], v[192:195], v[208:211], v[116:119]
	v_mfma_f32_16x16x32_bf16 v[112:115], v[200:203], v[208:211], v[112:115]
	v_mfma_f32_16x16x32_bf16 v[100:103], v[192:195], v[216:219], v[100:103]
	v_mfma_f32_16x16x32_bf16 v[96:99], v[200:203], v[216:219], v[96:99]
	v_mfma_f32_16x16x32_bf16 v[84:87], v[192:195], v[224:227], v[84:87]
	v_mfma_f32_16x16x32_bf16 v[80:83], v[200:203], v[224:227], v[80:83]
	v_mfma_f32_16x16x32_bf16 v[68:71], v[192:195], v[232:235], v[68:71]
	v_mfma_f32_16x16x32_bf16 v[64:67], v[200:203], v[232:235], v[64:67]
	s_setprio 0
	s_barrier
	s_add_i32 s24, s24, s29
	v_lshl_add_u64 v[170:171], s[46:47], 0, v[128:129]
	s_mov_b32 m0, s24
	ds_read_b128 v[204:207], v153 offset:16384
	ds_read_b128 v[208:211], v153 offset:17408
	ds_read_b128 v[212:215], v153 offset:18432
	ds_read_b128 v[216:219], v153 offset:19456
	ds_read_b128 v[220:223], v153 offset:20480
	ds_read_b128 v[224:227], v153 offset:21504
	ds_read_b128 v[228:231], v153 offset:22528
	ds_read_b128 v[232:235], v153 offset:23552
	global_load_lds_dwordx4 v[170:171], off
	s_add_i32 m0, s24, 0x2000
	s_add_u32 s24, s46, 0x30000
	v_lshl_add_u64 v[236:237], s[46:47], 0, v[130:131]
	s_addc_u32 s25, s47, 0
	s_add_i32 s44, s51, s29
	global_load_lds_dwordx4 v[236:237], off
	v_lshl_add_u64 v[238:239], s[24:25], 0, v[128:129]
	s_mov_b32 m0, s44
	v_lshl_add_u64 v[240:241], s[68:69], 0, v[130:131]
	global_load_lds_dwordx4 v[238:239], off
	v_lshl_add_u64 v[238:239], s[24:25], 0, v[130:131]
	s_add_i32 m0, s44, 0x2000
	s_nop 0
	global_load_lds_dwordx4 v[238:239], off
	v_lshl_add_u64 v[238:239], s[68:69], 0, v[128:129]
	s_mov_b32 m0, s71
	s_nop 0
	global_load_lds_dwordx4 v[238:239], off
	s_mov_b32 m0, s87
	s_nop 0
	global_load_lds_dwordx4 v[240:241], off
	s_waitcnt vmcnt(44)
	s_waitcnt lgkmcnt(0)
	s_barrier
; #define PG8_STAGE(bufoff, gbase, voff) do { _Pragma("unroll") for (int _i = 0; _i < 2; ++_i) \
;         __builtin_amdgcn_global_load_lds((const unsigned*)((const char*)(gbase) + (voff)[_i]), (PG8_LAS unsigned*)(lds + (bufoff) + ldsw + _i * 8192), 16, 0, 0); } while (0)
; #define PG8_LDA(dst, b, h) do { _Pragma("unroll") for (int m = 0; m < 4; ++m) _Pragma("unroll") for (int k = 0; k < 2; ++k) dst[m][k] = *(const PG8_LAS bf16x8*)(lds + PG8_SA(b, h) + aoff + m * 2048 + k * 1024); } while (0)
; #define PG8_LDB(dst, b, h) do { _Pragma("unroll") for (int n = 0; n < 2; ++n) _Pragma("unroll") for (int k = 0; k < 2; ++k) dst[n][k] = *(const PG8_LAS bf16x8*)(lds + PG8_SB(b, h) + boff + n * 2048 + k * 1024); } while (0)
; #define PG8_MMA(ai, bj, At, Bt) do { __builtin_amdgcn_s_setprio(1); _Pragma("unroll") for (int m = 0; m < 4; ++m) _Pragma("unroll") for (int n = 0; n < 2; ++n) _Pragma("unroll") for (int k = 0; k < 2; ++k) \
;         acc[ai][bj][m][n] = __builtin_amdgcn_mfma_f32_16x16x32_bf16(Bt[n][k], At[m][k], acc[ai][bj][m][n], 0, 0, 0); __builtin_amdgcn_s_setprio(0); } while (0)
; #define PG8_WAIT_V(n) asm volatile("s_waitcnt vmcnt(" #n ")" ::: "memory")
; #define PG8_WAIT_L(n) asm volatile("s_waitcnt lgkmcnt(" #n ")" ::: "memory")
; #define PG8_BAR __builtin_amdgcn_s_barrier()
; #define PG8_SCHED __builtin_amdgcn_sched_barrier(0)
; template <class Epi, class Sched, bool ALIGN_EPI = false, bool SP2 = false>
; __device__ __forceinline__ void gemm_phase(PG8_LAS unsigned char* lds, const Gemm g, const Sched& S, const Epi& E) {
;     ...
;             PG8_WAIT_V(8); PG8_WAIT_L(0); PG8_BAR; PG8_MMA(1, 0, At, B0); PG8_MMA(1, 1, At, B1); PG8_BAR; PG8_SCHED;
;             PG8_LDB(B0, 1, 0); PG8_LDB(B1, 1, 1); PG8_SCHED; PG8_LDA(At, 1, 0); PG8_STAGE(PG8_SA(0, 1), a2 + hstep, voffA);
;             PG8_WAIT_V(8); PG8_WAIT_L(0); PG8_BAR; PG8_MMA(0, 0, At, B0); PG8_MMA(0, 1, At, B1); PG8_BAR; PG8_SCHED;
	s_setprio 1
	s_waitcnt lgkmcnt(0)
	v_mfma_f32_16x16x32_bf16 v[60:63], v[146:149], v[204:207], 0
	v_mfma_f32_16x16x32_bf16 v[56:59], v[158:161], v[204:207], 0
	v_mfma_f32_16x16x32_bf16 v[44:47], v[146:149], v[212:215], 0
	v_mfma_f32_16x16x32_bf16 v[40:43], v[158:161], v[212:215], 0
	v_mfma_f32_16x16x32_bf16 v[28:31], v[146:149], v[220:223], 0
	v_mfma_f32_16x16x32_bf16 v[24:27], v[158:161], v[220:223], 0
	v_mfma_f32_16x16x32_bf16 v[12:15], v[146:149], v[228:231], 0
	v_mfma_f32_16x16x32_bf16 v[8:11], v[158:161], v[228:231], 0
	v_mfma_f32_16x16x32_bf16 v[60:63], v[154:157], v[208:211], v[60:63]
	v_mfma_f32_16x16x32_bf16 v[56:59], v[162:165], v[208:211], v[56:59]
	v_mfma_f32_16x16x32_bf16 v[44:47], v[154:157], v[216:219], v[44:47]
	v_mfma_f32_16x16x32_bf16 v[40:43], v[162:165], v[216:219], v[40:43]
	v_mfma_f32_16x16x32_bf16 v[28:31], v[154:157], v[224:227], v[28:31]
	v_mfma_f32_16x16x32_bf16 v[24:27], v[162:165], v[224:227], v[24:27]
	v_mfma_f32_16x16x32_bf16 v[12:15], v[154:157], v[232:235], v[12:15]
	v_mfma_f32_16x16x32_bf16 v[8:11], v[162:165], v[232:235], v[8:11]
	s_setprio 0
	s_setprio 1
	v_mfma_f32_16x16x32_bf16 v[52:55], v[166:169], v[204:207], 0
	v_mfma_f32_16x16x32_bf16 v[48:51], v[196:199], v[204:207], 0
	v_mfma_f32_16x16x32_bf16 v[36:39], v[166:169], v[212:215], 0
	v_mfma_f32_16x16x32_bf16 v[32:35], v[196:199], v[212:215], 0
	v_mfma_f32_16x16x32_bf16 v[20:23], v[166:169], v[220:223], 0
	v_mfma_f32_16x16x32_bf16 v[16:19], v[196:199], v[220:223], 0
	v_mfma_f32_16x16x32_bf16 v[4:7], v[166:169], v[228:231], 0
	v_mfma_f32_16x16x32_bf16 v[0:3], v[196:199], v[228:231], 0
	v_mfma_f32_16x16x32_bf16 v[52:55], v[192:195], v[208:211], v[52:55]
	v_mfma_f32_16x16x32_bf16 v[48:51], v[200:203], v[208:211], v[48:51]
	v_mfma_f32_16x16x32_bf16 v[36:39], v[192:195], v[216:219], v[36:39]
	v_mfma_f32_16x16x32_bf16 v[32:35], v[200:203], v[216:219], v[32:35]
	v_mfma_f32_16x16x32_bf16 v[20:23], v[192:195], v[224:227], v[20:23]
	v_mfma_f32_16x16x32_bf16 v[16:19], v[200:203], v[224:227], v[16:19]
	v_mfma_f32_16x16x32_bf16 v[4:7], v[192:195], v[232:235], v[4:7]
	v_mfma_f32_16x16x32_bf16 v[0:3], v[200:203], v[232:235], v[0:3]
	s_setprio 0
	s_barrier
	s_add_i32 s44, 0, 0x18000
	s_add_i32 s45, 0, 0x1c000
	v_add_u32_e32 v162, s44, v150
	v_add_u32_e32 v184, s45, v150
	ds_read_b128 v[146:149], v162
	ds_read_b128 v[154:157], v162 offset:1024
	ds_read_b128 v[158:161], v162 offset:2048
	ds_read_b128 v[162:165], v162 offset:3072
	ds_read_b128 v[166:169], v184
	ds_read_b128 v[192:195], v184 offset:1024
	ds_read_b128 v[196:199], v184 offset:2048
	ds_read_b128 v[200:203], v184 offset:3072
	s_add_u32 s24, s68, 0x30000
	s_addc_u32 s25, s69, 0
	s_mov_b32 m0, s88
	v_lshl_add_u64 v[242:243], s[24:25], 0, v[128:129]
	ds_read_b128 v[204:207], v153 offset:32768
	ds_read_b128 v[208:211], v153 offset:33792
	ds_read_b128 v[212:215], v153 offset:34816
	ds_read_b128 v[216:219], v153 offset:35840
	ds_read_b128 v[220:223], v153 offset:36864
	ds_read_b128 v[224:227], v153 offset:37888
	ds_read_b128 v[228:231], v153 offset:38912
	ds_read_b128 v[232:235], v153 offset:39936
	global_load_lds_dwordx4 v[242:243], off
	v_lshl_add_u64 v[242:243], s[24:25], 0, v[130:131]
	s_mov_b32 m0, s89
	s_nop 0
	global_load_lds_dwordx4 v[242:243], off
	s_waitcnt vmcnt(8)
	s_waitcnt lgkmcnt(0)
	s_barrier
	s_setprio 1
	s_waitcnt lgkmcnt(0)
	v_mfma_f32_16x16x32_bf16 v[124:127], v[146:149], v[204:207], v[124:127]
	v_mfma_f32_16x16x32_bf16 v[120:123], v[158:161], v[204:207], v[120:123]
	v_mfma_f32_16x16x32_bf16 v[108:111], v[146:149], v[212:215], v[108:111]
	v_mfma_f32_16x16x32_bf16 v[104:107], v[158:161], v[212:215], v[104:107]
	v_mfma_f32_16x16x32_bf16 v[92:95], v[146:149], v[220:223], v[92:95]
	v_mfma_f32_16x16x32_bf16 v[88:91], v[158:161], v[220:223], v[88:91]
	v_mfma_f32_16x16x32_bf16 v[76:79], v[146:149], v[228:231], v[76:79]
	v_mfma_f32_16x16x32_bf16 v[72:75], v[158:161], v[228:231], v[72:75]
	v_mfma_f32_16x16x32_bf16 v[124:127], v[154:157], v[208:211], v[124:127]
	v_mfma_f32_16x16x32_bf16 v[120:123], v[162:165], v[208:211], v[120:123]
	v_mfma_f32_16x16x32_bf16 v[108:111], v[154:157], v[216:219], v[108:111]
	v_mfma_f32_16x16x32_bf16 v[104:107], v[162:165], v[216:219], v[104:107]
	v_mfma_f32_16x16x32_bf16 v[92:95], v[154:157], v[224:227], v[92:95]
	v_mfma_f32_16x16x32_bf16 v[88:91], v[162:165], v[224:227], v[88:91]
	v_mfma_f32_16x16x32_bf16 v[76:79], v[154:157], v[232:235], v[76:79]
	v_mfma_f32_16x16x32_bf16 v[72:75], v[162:165], v[232:235], v[72:75]
	s_setprio 0
	s_setprio 1
	v_mfma_f32_16x16x32_bf16 v[116:119], v[166:169], v[204:207], v[116:119]
	v_mfma_f32_16x16x32_bf16 v[112:115], v[196:199], v[204:207], v[112:115]
	v_mfma_f32_16x16x32_bf16 v[100:103], v[166:169], v[212:215], v[100:103]
	v_mfma_f32_16x16x32_bf16 v[96:99], v[196:199], v[212:215], v[96:99]
	v_mfma_f32_16x16x32_bf16 v[84:87], v[166:169], v[220:223], v[84:87]
	v_mfma_f32_16x16x32_bf16 v[80:83], v[196:199], v[220:223], v[80:83]
	v_mfma_f32_16x16x32_bf16 v[68:71], v[166:169], v[228:231], v[68:71]
	v_mfma_f32_16x16x32_bf16 v[64:67], v[196:199], v[228:231], v[64:67]
	v_mfma_f32_16x16x32_bf16 v[116:119], v[192:195], v[208:211], v[116:119]
	v_mfma_f32_16x16x32_bf16 v[112:115], v[200:203], v[208:211], v[112:115]
	v_mfma_f32_16x16x32_bf16 v[100:103], v[192:195], v[216:219], v[100:103]
	v_mfma_f32_16x16x32_bf16 v[96:99], v[200:203], v[216:219], v[96:99]
	v_mfma_f32_16x16x32_bf16 v[84:87], v[192:195], v[224:227], v[84:87]
	v_mfma_f32_16x16x32_bf16 v[80:83], v[200:203], v[224:227], v[80:83]
	v_mfma_f32_16x16x32_bf16 v[68:71], v[192:195], v[232:235], v[68:71]
	v_mfma_f32_16x16x32_bf16 v[64:67], v[200:203], v[232:235], v[64:67]
	s_setprio 0
	s_barrier
; #define PG8_STAGE(bufoff, gbase, voff) do { _Pragma("unroll") for (int _i = 0; _i < 2; ++_i) \
;         __builtin_amdgcn_global_load_lds((const unsigned*)((const char*)(gbase) + (voff)[_i]), (PG8_LAS unsigned*)(lds + (bufoff) + ldsw + _i * 8192), 16, 0, 0); } while (0)
; #define PG8_LDA(dst, b, h) do { _Pragma("unroll") for (int m = 0; m < 4; ++m) _Pragma("unroll") for (int k = 0; k < 2; ++k) dst[m][k] = *(const PG8_LAS bf16x8*)(lds + PG8_SA(b, h) + aoff + m * 2048 + k * 1024); } while (0)
; #define PG8_MMA(ai, bj, At, Bt) do { __builtin_amdgcn_s_setprio(1); _Pragma("unroll") for (int m = 0; m < 4; ++m) _Pragma("unroll") for (int n = 0; n < 2; ++n) _Pragma("unroll") for (int k = 0; k < 2; ++k) \
;         acc[ai][bj][m][n] = __builtin_amdgcn_mfma_f32_16x16x32_bf16(Bt[n][k], At[m][k], acc[ai][bj][m][n], 0, 0, 0); __builtin_amdgcn_s_setprio(0); } while (0)
; #define PG8_WAIT_V(n) asm volatile("s_waitcnt vmcnt(" #n ")" ::: "memory")
; #define PG8_WAIT_L(n) asm volatile("s_waitcnt lgkmcnt(" #n ")" ::: "memory")
; #define PG8_BAR __builtin_amdgcn_s_barrier()
; #define PG8_SCHED __builtin_amdgcn_sched_barrier(0)
; template <class Epi, class Sched, bool ALIGN_EPI = false, bool SP2 = false>
; __device__ __forceinline__ void gemm_phase(PG8_LAS unsigned char* lds, const Gemm g, const Sched& S, const Epi& E) {
;     ...
;             PG8_LDA(At, 1, 1); PG8_STAGE(PG8_SB(1, 0), b3, voffB); PG8_STAGE(PG8_SB(1, 1), b3 + hstep, voffB); PG8_STAGE(PG8_SA(1, 0), a3, voffA);
;             PG8_WAIT_V(8); PG8_WAIT_L(0); PG8_BAR; PG8_MMA(1, 0, At, B0); PG8_MMA(1, 1, At, B1); PG8_BAR; PG8_SCHED;
	s_add_i32 s24, s44, s29
	v_lshl_add_u64 v[170:171], v[170:171], 0, s[14:15]
	s_mov_b32 m0, s24
	ds_read_b128 v[204:207], v153 offset:49152
	ds_read_b128 v[208:211], v153 offset:50176
	ds_read_b128 v[212:215], v153 offset:51200
	ds_read_b128 v[216:219], v153 offset:52224
	ds_read_b128 v[220:223], v153 offset:53248
	ds_read_b128 v[224:227], v153 offset:54272
	ds_read_b128 v[228:231], v153 offset:55296
	ds_read_b128 v[232:235], v153 offset:56320
	global_load_lds_dwordx4 v[170:171], off
	s_add_i32 m0, s24, 0x2000
	s_add_u32 s24, s46, 0x30080
	v_lshl_add_u64 v[170:171], v[236:237], 0, s[14:15]
	s_addc_u32 s25, s47, 0
	s_add_i32 s44, s45, s29
	global_load_lds_dwordx4 v[170:171], off
	v_lshl_add_u64 v[170:171], s[24:25], 0, v[128:129]
	s_mov_b32 m0, s44
	s_nop 0
	global_load_lds_dwordx4 v[170:171], off
	v_lshl_add_u64 v[170:171], s[24:25], 0, v[130:131]
	s_add_i32 m0, s44, 0x2000
	s_nop 0
	global_load_lds_dwordx4 v[170:171], off
	v_lshl_add_u64 v[170:171], v[238:239], 0, s[14:15]
	s_mov_b32 m0, s91
	s_nop 0
	global_load_lds_dwordx4 v[170:171], off
	v_lshl_add_u64 v[170:171], v[240:241], 0, s[14:15]
	s_mov_b32 m0, s92
	s_nop 0
	global_load_lds_dwordx4 v[170:171], off
	s_waitcnt vmcnt(8)
	s_waitcnt lgkmcnt(0)
	s_barrier
	s_setprio 1
	s_waitcnt lgkmcnt(0)
	v_mfma_f32_16x16x32_bf16 v[60:63], v[146:149], v[204:207], v[60:63]
	v_mfma_f32_16x16x32_bf16 v[56:59], v[158:161], v[204:207], v[56:59]
	v_mfma_f32_16x16x32_bf16 v[44:47], v[146:149], v[212:215], v[44:47]
	v_mfma_f32_16x16x32_bf16 v[40:43], v[158:161], v[212:215], v[40:43]
	v_mfma_f32_16x16x32_bf16 v[28:31], v[146:149], v[220:223], v[28:31]
	v_mfma_f32_16x16x32_bf16 v[24:27], v[158:161], v[220:223], v[24:27]
	v_mfma_f32_16x16x32_bf16 v[12:15], v[146:149], v[228:231], v[12:15]
	v_mfma_f32_16x16x32_bf16 v[8:11], v[158:161], v[228:231], v[8:11]
	v_mfma_f32_16x16x32_bf16 v[60:63], v[154:157], v[208:211], v[60:63]
	v_mfma_f32_16x16x32_bf16 v[56:59], v[162:165], v[208:211], v[56:59]
	v_mfma_f32_16x16x32_bf16 v[44:47], v[154:157], v[216:219], v[44:47]
	v_mfma_f32_16x16x32_bf16 v[40:43], v[162:165], v[216:219], v[40:43]
	v_mfma_f32_16x16x32_bf16 v[28:31], v[154:157], v[224:227], v[28:31]
	v_mfma_f32_16x16x32_bf16 v[24:27], v[162:165], v[224:227], v[24:27]
	v_mfma_f32_16x16x32_bf16 v[12:15], v[154:157], v[232:235], v[12:15]
	v_mfma_f32_16x16x32_bf16 v[8:11], v[162:165], v[232:235], v[8:11]
	s_setprio 0
	s_setprio 1
	v_mfma_f32_16x16x32_bf16 v[52:55], v[166:169], v[204:207], v[52:55]
	v_mfma_f32_16x16x32_bf16 v[48:51], v[196:199], v[204:207], v[48:51]
	v_mfma_f32_16x16x32_bf16 v[36:39], v[166:169], v[212:215], v[36:39]
	v_mfma_f32_16x16x32_bf16 v[32:35], v[196:199], v[212:215], v[32:35]
	v_mfma_f32_16x16x32_bf16 v[20:23], v[166:169], v[220:223], v[20:23]
	v_mfma_f32_16x16x32_bf16 v[16:19], v[196:199], v[220:223], v[16:19]
	v_mfma_f32_16x16x32_bf16 v[4:7], v[166:169], v[228:231], v[4:7]
	v_mfma_f32_16x16x32_bf16 v[0:3], v[196:199], v[228:231], v[0:3]
	v_mfma_f32_16x16x32_bf16 v[52:55], v[192:195], v[208:211], v[52:55]
	v_mfma_f32_16x16x32_bf16 v[48:51], v[200:203], v[208:211], v[48:51]
	v_mfma_f32_16x16x32_bf16 v[36:39], v[192:195], v[216:219], v[36:39]
	v_mfma_f32_16x16x32_bf16 v[32:35], v[200:203], v[216:219], v[32:35]
	v_mfma_f32_16x16x32_bf16 v[20:23], v[192:195], v[224:227], v[20:23]
	v_mfma_f32_16x16x32_bf16 v[16:19], v[200:203], v[224:227], v[16:19]
	v_mfma_f32_16x16x32_bf16 v[4:7], v[192:195], v[232:235], v[4:7]
	v_mfma_f32_16x16x32_bf16 v[0:3], v[200:203], v[232:235], v[0:3]
	s_setprio 0
	s_barrier
	s_add_i32 s50, s50, 2
	s_add_u32 s22, s22, 0x100
	s_addc_u32 s33, s33, 0
	s_cmp_gt_u32 s50, 9
	s_mov_b64 s[44:45], s[42:43]

; #define PG8_STAGE(bufoff, gbase, voff) do { _Pragma("unroll") for (int _i = 0; _i < 2; ++_i) \
;         __builtin_amdgcn_global_load_lds((const unsigned*)((const char*)(gbase) + (voff)[_i]), (PG8_LAS unsigned*)(lds + (bufoff) + ldsw + _i * 8192), 16, 0, 0); } while (0)
; #define PG8_WAIT_V(n) asm volatile("s_waitcnt vmcnt(" #n ")" ::: "memory")
; #define PG8_BAR __builtin_amdgcn_s_barrier()
; template <class Epi, class Sched, bool ALIGN_EPI = false, bool SP2 = false>
; __device__ __forceinline__ void gemm_phase(PG8_LAS unsigned char* lds, const Gemm g, const Sched& S, const Epi& E) {
;     ...
;     for (int i = 0; i < 2; ++i) { int R, C; stage_rc(tid * 16 + i * 8192, R, C); const int Rb = Epi::PERM ? ((R & ~31) + perm32(R & 31)) : R;
;         voffA[i] = (unsigned)(R * K + C) * 2u; voffB[i] = (unsigned)(Rb * K + C) * 2u; }
;     const size_t kstep = (size_t)(BK * 2);
;     const size_t hstep = (size_t)HALF * K * 2;
;     const size_t tstep = 2 * hstep;
;     const unsigned ldsw = (unsigned)wid * 1024u;
;     const int aoff = lds_byte(wr * 64 + fr, fq * 8), boff = lds_byte(wc * 32 + fr, fq * 8);
;     ...
;         PG8_WAIT_V(2); PG8_BAR;
;         PG8_STAGE(PG8_SB(1, 0), cB + kstep, voffB); PG8_STAGE(PG8_SA(1, 0), cA + kstep, voffA); PG8_STAGE(PG8_SB(1, 1), cB + hstep + kstep, voffB);
;         PG8_WAIT_V(6); PG8_BAR;
.LBB0_169:
	s_and_b32 s1, s1, 3
	s_add_i32 m0, s73, 0x18000
	v_lshl_add_u64 v[6:7], v[6:7], 0, s[14:15]
	s_lshl_b32 s5, s4, 13
	s_lshl_b32 s10, s1, 12
	s_waitcnt vmcnt(2)
	s_barrier
	global_load_lds_dwordx4 v[6:7], off
	v_lshl_add_u64 v[4:5], v[4:5], 0, s[14:15]
	s_add_i32 m0, s73, 0x1a000
	s_add_i32 s90, s73, 0x8000
	s_add_i32 s91, s73, 0xa000
	global_load_lds_dwordx4 v[4:5], off
	v_lshl_add_u64 v[0:1], v[0:1], 0, s[14:15]
	s_mov_b32 m0, s90
	s_add_u32 s20, s58, 0x40080
	global_load_lds_dwordx4 v[0:1], off
	v_lshl_add_u64 v[0:1], v[2:3], 0, s[14:15]
	s_mov_b32 m0, s91
	s_addc_u32 s21, s59, 0
	global_load_lds_dwordx4 v[0:1], off
	s_add_i32 m0, s73, 0x1c000
	v_lshl_add_u64 v[0:1], s[20:21], 0, v[142:143]
	global_load_lds_dwordx4 v[0:1], off
	v_lshl_add_u64 v[0:1], s[20:21], 0, v[146:147]
	s_add_i32 m0, s73, 0x1e000
	s_cmpk_lt_u32 s0, 0x100
	global_load_lds_dwordx4 v[0:1], off
	v_bfe_u32 v1, v8, 4, 2
	v_and_b32_e32 v0, 15, v8
	v_lshlrev_b32_e32 v3, 4, v1
	v_lshl_or_b32 v149, s4, 6, v0
	v_lshl_or_b32 v0, v0, 6, v3
	v_lshlrev_b32_e32 v3, 2, v8
	v_and_b32_e32 v3, 32, v3
	v_bitop3_b32 v4, v0, s5, v3 bitop3:0xde
	v_bitop3_b32 v192, v0, s10, v3 bitop3:0xde
	v_lshlrev_b32_e32 v0, 14, v9
	v_and_b32_e32 v0, 0xffff8000, v0
	v_lshlrev_b32_e32 v2, 3, v1
	v_cmp_eq_u32_e64 s[40:41], 0, v1
	v_lshl_add_u32 v0, v10, 11, v0
	v_and_b32_e32 v1, 1, v9
	v_lshl_or_b32 v0, v1, 6, v0
	v_lshl_add_u32 v154, v11, 1, v0
	v_lshlrev_b32_e32 v0, 14, v12
	v_lshl_or_b32 v148, s1, 5, v2
	v_and_b32_e32 v0, 0xffff8000, v0
	s_waitcnt vmcnt(0)
	v_lshlrev_b32_e32 v132, 1, v148
	v_lshl_add_u32 v0, v13, 11, v0
	v_and_b32_e32 v1, 1, v12
	s_cselect_b64 s[4:5], -1, 0
	s_cmp_eq_u32 s1, 0
	v_lshl_add_u64 v[150:151], s[16:17], 0, v[132:133]
	v_or_b32_e32 v132, 0x100, v132
	v_lshl_or_b32 v0, v1, 6, v0
	s_mov_b32 s92, 0
	s_cselect_b64 s[20:21], -1, 0
	s_ashr_i32 s93, s83, 31
	s_ashr_i32 s94, s84, 31
	v_lshl_add_u64 v[152:153], s[16:17], 0, v[132:133]
	v_mov_b32_e32 v155, v133
	v_lshl_add_u32 v156, v14, 1, v0
	v_mov_b32_e32 v157, v133
	v_add_u32_e32 v193, 0, v4
	s_barrier
	s_branch .LBB0_172

; #define PG8_STAGE(bufoff, gbase, voff) do { _Pragma("unroll") for (int _i = 0; _i < 2; ++_i) \
;         __builtin_amdgcn_global_load_lds((const unsigned*)((const char*)(gbase) + (voff)[_i]), (PG8_LAS unsigned*)(lds + (bufoff) + ldsw + _i * 8192), 16, 0, 0); } while (0)
; #define PG8_LDA(dst, b, h) do { _Pragma("unroll") for (int m = 0; m < 4; ++m) _Pragma("unroll") for (int k = 0; k < 2; ++k) dst[m][k] = *(const PG8_LAS bf16x8*)(lds + PG8_SA(b, h) + aoff + m * 2048 + k * 1024); } while (0)
; #define PG8_LDB(dst, b, h) do { _Pragma("unroll") for (int n = 0; n < 2; ++n) _Pragma("unroll") for (int k = 0; k < 2; ++k) dst[n][k] = *(const PG8_LAS bf16x8*)(lds + PG8_SB(b, h) + boff + n * 2048 + k * 1024); } while (0)
; #define PG8_WAIT_V(n) asm volatile("s_waitcnt vmcnt(" #n ")" ::: "memory")
; #define PG8_WAIT_L(n) asm volatile("s_waitcnt lgkmcnt(" #n ")" ::: "memory")
; #define PG8_BAR __builtin_amdgcn_s_barrier()
; #define PG8_SCHED __builtin_amdgcn_sched_barrier(0)
; template <class Epi, class Sched, bool ALIGN_EPI = false, bool SP2 = false>
; __device__ __forceinline__ void gemm_phase(PG8_LAS unsigned char* lds, const Gemm g, const Sched& S, const Epi& E) {
;     ...
;         const char* nA = has_next ? (const char*)g.A + (size_t)nxt.pm * tstep : cA; const char* nB = has_next ? (const char*)g.Bt + (size_t)nxt.pn * tstep : cB;
;         for (int t = 0; t < nt; t += 2) {
;             const bool last = (t == nt - 2);
;             const char* a1 = cA + (size_t)(t + 1) * kstep;
;             const char* a2 = last ? nA : cA + (size_t)(t + 2) * kstep; const char* b2 = last ? nB : cB + (size_t)(t + 2) * kstep;
;             const char* a3 = a2 + kstep; const char* b3 = b2 + kstep;
;             if (last && has_next) S.a_ready(nxt);
;             if constexpr (SP2) {
;             PG8_LDB(B0, 0, 0); PG8_LDB(B1, 0, 1); PG8_SCHED; PG8_LDA(At, 0, 0); PG8_STAGE(PG8_SA(1, 1), a1 + hstep, voffA);
;             PG8_WAIT_V(8); PG8_WAIT_L(0); PG8_BAR; PG8_MMA(0, 0, At, B0); PG8_MMA(0, 1, At, B1); PG8_BAR; PG8_SCHED;
;             PG8_LDA(At, 0, 1); PG8_STAGE(PG8_SB(0, 0), b2, voffB); PG8_STAGE(PG8_SB(0, 1), b2 + hstep, voffB); PG8_STAGE(PG8_SA(0, 0), a2, voffA);
;             PG8_WAIT_V(8); PG8_WAIT_L(0); PG8_BAR; PG8_MMA(1, 0, At, B0); PG8_MMA(1, 1, At, B1); PG8_BAR; PG8_SCHED;
.LBB0_174:
	s_ashr_i32 s39, s38, 31
	s_lshl_b64 s[0:1], s[38:39], 19
	s_add_u32 s48, s23, s0
	s_addc_u32 s49, s12, s1
	s_and_b64 s[0:1], s[42:43], exec
	s_cselect_b32 s0, s49, s57
	s_cselect_b32 s1, s48, s56
	s_ashr_i32 s37, s36, 31
	s_lshl_b64 s[24:25], s[36:37], 19
	s_add_u32 s52, s85, s24
	s_addc_u32 s53, s86, s25
	s_and_b64 s[24:25], s[42:43], exec
	s_cselect_b32 s10, s53, s59
	s_cselect_b32 s22, s52, s58
	s_add_u32 s56, s56, 0x40080
	s_addc_u32 s57, s57, 0
	s_add_u32 s33, s58, 0x100
	s_addc_u32 s37, s59, 0
	s_mov_b32 s39, -2
	s_waitcnt lgkmcnt(0)
	s_add_u32 s24, s56, 0xfffc0080
	s_addc_u32 s25, s57, -1
	s_add_i32 s45, 0, 0x10000
	s_cmp_eq_u32 s39, 12
	s_cselect_b32 s61, s0, s25
	s_cselect_b32 s60, s1, s24
	v_add_u32_e32 v132, s45, v192
	s_cselect_b32 s59, s10, s37
	s_cselect_b32 s58, s22, s33
	s_add_i32 s47, 0, 0x14000
	ds_read_b128 v[128:131], v132
	ds_read_b128 v[158:161], v132 offset:1024
	ds_read_b128 v[162:165], v132 offset:2048
	ds_read_b128 v[166:169], v132 offset:3072
	v_add_u32_e32 v132, s47, v192
	ds_read_b128 v[194:197], v132
	ds_read_b128 v[198:201], v132 offset:1024
	ds_read_b128 v[202:205], v132 offset:2048
	ds_read_b128 v[206:209], v132 offset:3072
	v_lshl_add_u64 v[170:171], s[56:57], 0, v[154:155]
	s_add_i32 m0, s73, 0xc000
	ds_read_b128 v[210:213], v193
	ds_read_b128 v[214:217], v193 offset:1024
	ds_read_b128 v[218:221], v193 offset:2048
	ds_read_b128 v[222:225], v193 offset:3072
	ds_read_b128 v[226:229], v193 offset:4096
	ds_read_b128 v[230:233], v193 offset:5120
	ds_read_b128 v[234:237], v193 offset:6144
	ds_read_b128 v[238:241], v193 offset:7168
	global_load_lds_dwordx4 v[170:171], off
	v_lshl_add_u64 v[170:171], s[56:57], 0, v[156:157]
	s_add_i32 m0, s73, 0xe000
	s_nop 0
	global_load_lds_dwordx4 v[170:171], off
	s_waitcnt vmcnt(32)
	s_waitcnt lgkmcnt(0)
	s_barrier
	s_setprio 1
	s_waitcnt lgkmcnt(0)
	v_mfma_f32_16x16x32_bf16 v[124:127], v[128:131], v[210:213], 0
	v_mfma_f32_16x16x32_bf16 v[120:123], v[162:165], v[210:213], 0
	v_mfma_f32_16x16x32_bf16 v[108:111], v[128:131], v[218:221], 0
	v_mfma_f32_16x16x32_bf16 v[104:107], v[162:165], v[218:221], 0
	v_mfma_f32_16x16x32_bf16 v[92:95], v[128:131], v[226:229], 0
	v_mfma_f32_16x16x32_bf16 v[88:91], v[162:165], v[226:229], 0
	v_mfma_f32_16x16x32_bf16 v[76:79], v[128:131], v[234:237], 0
	v_mfma_f32_16x16x32_bf16 v[72:75], v[162:165], v[234:237], 0
	v_mfma_f32_16x16x32_bf16 v[124:127], v[158:161], v[214:217], v[124:127]
	v_mfma_f32_16x16x32_bf16 v[120:123], v[166:169], v[214:217], v[120:123]
	v_mfma_f32_16x16x32_bf16 v[108:111], v[158:161], v[222:225], v[108:111]
	v_mfma_f32_16x16x32_bf16 v[104:107], v[166:169], v[222:225], v[104:107]
	v_mfma_f32_16x16x32_bf16 v[92:95], v[158:161], v[230:233], v[92:95]
	v_mfma_f32_16x16x32_bf16 v[88:91], v[166:169], v[230:233], v[88:91]
	v_mfma_f32_16x16x32_bf16 v[76:79], v[158:161], v[238:241], v[76:79]
	v_mfma_f32_16x16x32_bf16 v[72:75], v[166:169], v[238:241], v[72:75]
	s_setprio 0
	s_setprio 1
	v_mfma_f32_16x16x32_bf16 v[116:119], v[194:197], v[210:213], 0
	v_mfma_f32_16x16x32_bf16 v[112:115], v[202:205], v[210:213], 0
	v_mfma_f32_16x16x32_bf16 v[100:103], v[194:197], v[218:221], 0
	v_mfma_f32_16x16x32_bf16 v[96:99], v[202:205], v[218:221], 0
	v_mfma_f32_16x16x32_bf16 v[84:87], v[194:197], v[226:229], 0
	v_mfma_f32_16x16x32_bf16 v[80:83], v[202:205], v[226:229], 0
	v_mfma_f32_16x16x32_bf16 v[68:71], v[194:197], v[234:237], 0
	v_mfma_f32_16x16x32_bf16 v[64:67], v[202:205], v[234:237], 0
	v_mfma_f32_16x16x32_bf16 v[116:119], v[198:201], v[214:217], v[116:119]
	v_mfma_f32_16x16x32_bf16 v[112:115], v[206:209], v[214:217], v[112:115]
	v_mfma_f32_16x16x32_bf16 v[100:103], v[198:201], v[222:225], v[100:103]
	v_mfma_f32_16x16x32_bf16 v[96:99], v[206:209], v[222:225], v[96:99]
	v_mfma_f32_16x16x32_bf16 v[84:87], v[198:201], v[230:233], v[84:87]
	v_mfma_f32_16x16x32_bf16 v[80:83], v[206:209], v[230:233], v[80:83]
	v_mfma_f32_16x16x32_bf16 v[68:71], v[198:201], v[238:241], v[68:71]
	v_mfma_f32_16x16x32_bf16 v[64:67], v[206:209], v[238:241], v[64:67]
	s_setprio 0
	s_barrier
	s_add_i32 s24, s45, s29
	v_lshl_add_u64 v[170:171], s[58:59], 0, v[142:143]
	s_mov_b32 m0, s24
	ds_read_b128 v[210:213], v193 offset:16384
	ds_read_b128 v[214:217], v193 offset:17408
	ds_read_b128 v[218:221], v193 offset:18432
	ds_read_b128 v[222:225], v193 offset:19456
	ds_read_b128 v[226:229], v193 offset:20480
	ds_read_b128 v[230:233], v193 offset:21504
	ds_read_b128 v[234:237], v193 offset:22528
	ds_read_b128 v[238:241], v193 offset:23552
	global_load_lds_dwordx4 v[170:171], off
	s_add_i32 m0, s24, 0x2000
	s_add_u32 s24, s58, 0x40000
	v_lshl_add_u64 v[242:243], s[58:59], 0, v[146:147]
	s_addc_u32 s25, s59, 0
	s_add_i32 s45, s47, s29
	global_load_lds_dwordx4 v[242:243], off
	v_lshl_add_u64 v[244:245], s[24:25], 0, v[142:143]
	s_mov_b32 m0, s45
	v_lshl_add_u64 v[246:247], s[60:61], 0, v[144:145]
	global_load_lds_dwordx4 v[244:245], off
	v_lshl_add_u64 v[244:245], s[24:25], 0, v[146:147]
	s_add_i32 m0, s45, 0x2000
	s_nop 0
	global_load_lds_dwordx4 v[244:245], off
	v_lshl_add_u64 v[244:245], s[60:61], 0, v[140:141]
	s_mov_b32 m0, s73
	s_nop 0
	global_load_lds_dwordx4 v[244:245], off
	s_mov_b32 m0, s87
	s_nop 0
	global_load_lds_dwordx4 v[246:247], off
	s_waitcnt vmcnt(40)
	s_waitcnt lgkmcnt(0)
	s_barrier
; #define PG8_STAGE(bufoff, gbase, voff) do { _Pragma("unroll") for (int _i = 0; _i < 2; ++_i) \
;         __builtin_amdgcn_global_load_lds((const unsigned*)((const char*)(gbase) + (voff)[_i]), (PG8_LAS unsigned*)(lds + (bufoff) + ldsw + _i * 8192), 16, 0, 0); } while (0)
; #define PG8_LDA(dst, b, h) do { _Pragma("unroll") for (int m = 0; m < 4; ++m) _Pragma("unroll") for (int k = 0; k < 2; ++k) dst[m][k] = *(const PG8_LAS bf16x8*)(lds + PG8_SA(b, h) + aoff + m * 2048 + k * 1024); } while (0)
; #define PG8_LDB(dst, b, h) do { _Pragma("unroll") for (int n = 0; n < 2; ++n) _Pragma("unroll") for (int k = 0; k < 2; ++k) dst[n][k] = *(const PG8_LAS bf16x8*)(lds + PG8_SB(b, h) + boff + n * 2048 + k * 1024); } while (0)
; #define PG8_MMA(ai, bj, At, Bt) do { __builtin_amdgcn_s_setprio(1); _Pragma("unroll") for (int m = 0; m < 4; ++m) _Pragma("unroll") for (int n = 0; n < 2; ++n) _Pragma("unroll") for (int k = 0; k < 2; ++k) \
;         acc[ai][bj][m][n] = __builtin_amdgcn_mfma_f32_16x16x32_bf16(Bt[n][k], At[m][k], acc[ai][bj][m][n], 0, 0, 0); __builtin_amdgcn_s_setprio(0); } while (0)
; #define PG8_WAIT_V(n) asm volatile("s_waitcnt vmcnt(" #n ")" ::: "memory")
; #define PG8_WAIT_L(n) asm volatile("s_waitcnt lgkmcnt(" #n ")" ::: "memory")
; #define PG8_BAR __builtin_amdgcn_s_barrier()
; #define PG8_SCHED __builtin_amdgcn_sched_barrier(0)
; template <class Epi, class Sched, bool ALIGN_EPI = false, bool SP2 = false>
; __device__ __forceinline__ void gemm_phase(PG8_LAS unsigned char* lds, const Gemm g, const Sched& S, const Epi& E) {
;     ...
;             PG8_WAIT_V(8); PG8_WAIT_L(0); PG8_BAR; PG8_MMA(1, 0, At, B0); PG8_MMA(1, 1, At, B1); PG8_BAR; PG8_SCHED;
;             PG8_LDB(B0, 1, 0); PG8_LDB(B1, 1, 1); PG8_SCHED; PG8_LDA(At, 1, 0); PG8_STAGE(PG8_SA(0, 1), a2 + hstep, voffA);
;             PG8_WAIT_V(8); PG8_WAIT_L(0); PG8_BAR; PG8_MMA(0, 0, At, B0); PG8_MMA(0, 1, At, B1); PG8_BAR; PG8_SCHED;
	s_setprio 1
	s_waitcnt lgkmcnt(0)
	v_mfma_f32_16x16x32_bf16 v[60:63], v[128:131], v[210:213], 0
	v_mfma_f32_16x16x32_bf16 v[56:59], v[162:165], v[210:213], 0
	v_mfma_f32_16x16x32_bf16 v[44:47], v[128:131], v[218:221], 0
	v_mfma_f32_16x16x32_bf16 v[40:43], v[162:165], v[218:221], 0
	v_mfma_f32_16x16x32_bf16 v[28:31], v[128:131], v[226:229], 0
	v_mfma_f32_16x16x32_bf16 v[24:27], v[162:165], v[226:229], 0
	v_mfma_f32_16x16x32_bf16 v[12:15], v[128:131], v[234:237], 0
	v_mfma_f32_16x16x32_bf16 v[8:11], v[162:165], v[234:237], 0
	v_mfma_f32_16x16x32_bf16 v[60:63], v[158:161], v[214:217], v[60:63]
	v_mfma_f32_16x16x32_bf16 v[56:59], v[166:169], v[214:217], v[56:59]
	v_mfma_f32_16x16x32_bf16 v[44:47], v[158:161], v[222:225], v[44:47]
	v_mfma_f32_16x16x32_bf16 v[40:43], v[166:169], v[222:225], v[40:43]
	v_mfma_f32_16x16x32_bf16 v[28:31], v[158:161], v[230:233], v[28:31]
	v_mfma_f32_16x16x32_bf16 v[24:27], v[166:169], v[230:233], v[24:27]
	v_mfma_f32_16x16x32_bf16 v[12:15], v[158:161], v[238:241], v[12:15]
	v_mfma_f32_16x16x32_bf16 v[8:11], v[166:169], v[238:241], v[8:11]
	s_setprio 0
	s_setprio 1
	v_mfma_f32_16x16x32_bf16 v[52:55], v[194:197], v[210:213], 0
	v_mfma_f32_16x16x32_bf16 v[48:51], v[202:205], v[210:213], 0
	v_mfma_f32_16x16x32_bf16 v[36:39], v[194:197], v[218:221], 0
	v_mfma_f32_16x16x32_bf16 v[32:35], v[202:205], v[218:221], 0
	v_mfma_f32_16x16x32_bf16 v[20:23], v[194:197], v[226:229], 0
	v_mfma_f32_16x16x32_bf16 v[16:19], v[202:205], v[226:229], 0
	v_mfma_f32_16x16x32_bf16 v[4:7], v[194:197], v[234:237], 0
	v_mfma_f32_16x16x32_bf16 v[0:3], v[202:205], v[234:237], 0
	v_mfma_f32_16x16x32_bf16 v[52:55], v[198:201], v[214:217], v[52:55]
	v_mfma_f32_16x16x32_bf16 v[48:51], v[206:209], v[214:217], v[48:51]
	v_mfma_f32_16x16x32_bf16 v[36:39], v[198:201], v[222:225], v[36:39]
	v_mfma_f32_16x16x32_bf16 v[32:35], v[206:209], v[222:225], v[32:35]
	v_mfma_f32_16x16x32_bf16 v[20:23], v[198:201], v[230:233], v[20:23]
	v_mfma_f32_16x16x32_bf16 v[16:19], v[206:209], v[230:233], v[16:19]
	v_mfma_f32_16x16x32_bf16 v[4:7], v[198:201], v[238:241], v[4:7]
	v_mfma_f32_16x16x32_bf16 v[0:3], v[206:209], v[238:241], v[0:3]
	s_setprio 0
	s_barrier
	s_add_i32 s45, 0, 0x18000
	v_add_u32_e32 v132, s45, v192
	s_add_i32 s47, 0, 0x1c000
	ds_read_b128 v[128:131], v132
	ds_read_b128 v[158:161], v132 offset:1024
	ds_read_b128 v[162:165], v132 offset:2048
	ds_read_b128 v[166:169], v132 offset:3072
	v_add_u32_e32 v132, s47, v192
	ds_read_b128 v[194:197], v132
	ds_read_b128 v[198:201], v132 offset:1024
	ds_read_b128 v[202:205], v132 offset:2048
	ds_read_b128 v[206:209], v132 offset:3072
	s_add_u32 s24, s60, 0x40000
	s_addc_u32 s25, s61, 0
	s_mov_b32 m0, s88
	v_lshl_add_u64 v[248:249], s[24:25], 0, v[140:141]
	ds_read_b128 v[210:213], v193 offset:32768
	ds_read_b128 v[214:217], v193 offset:33792
	ds_read_b128 v[218:221], v193 offset:34816
	ds_read_b128 v[222:225], v193 offset:35840
	ds_read_b128 v[226:229], v193 offset:36864
	ds_read_b128 v[230:233], v193 offset:37888
	ds_read_b128 v[234:237], v193 offset:38912
	ds_read_b128 v[238:241], v193 offset:39936
	global_load_lds_dwordx4 v[248:249], off
	v_lshl_add_u64 v[248:249], s[24:25], 0, v[144:145]
	s_mov_b32 m0, s89
	s_nop 0
	global_load_lds_dwordx4 v[248:249], off
	s_waitcnt vmcnt(8)
	s_waitcnt lgkmcnt(0)
	s_barrier
	s_setprio 1
	s_waitcnt lgkmcnt(0)
	v_mfma_f32_16x16x32_bf16 v[124:127], v[128:131], v[210:213], v[124:127]
	v_mfma_f32_16x16x32_bf16 v[120:123], v[162:165], v[210:213], v[120:123]
	v_mfma_f32_16x16x32_bf16 v[108:111], v[128:131], v[218:221], v[108:111]
	v_mfma_f32_16x16x32_bf16 v[104:107], v[162:165], v[218:221], v[104:107]
	v_mfma_f32_16x16x32_bf16 v[92:95], v[128:131], v[226:229], v[92:95]
	v_mfma_f32_16x16x32_bf16 v[88:91], v[162:165], v[226:229], v[88:91]
	v_mfma_f32_16x16x32_bf16 v[76:79], v[128:131], v[234:237], v[76:79]
	v_mfma_f32_16x16x32_bf16 v[72:75], v[162:165], v[234:237], v[72:75]
	v_mfma_f32_16x16x32_bf16 v[124:127], v[158:161], v[214:217], v[124:127]
	v_mfma_f32_16x16x32_bf16 v[120:123], v[166:169], v[214:217], v[120:123]
	v_mfma_f32_16x16x32_bf16 v[108:111], v[158:161], v[222:225], v[108:111]
	v_mfma_f32_16x16x32_bf16 v[104:107], v[166:169], v[222:225], v[104:107]
	v_mfma_f32_16x16x32_bf16 v[92:95], v[158:161], v[230:233], v[92:95]
	v_mfma_f32_16x16x32_bf16 v[88:91], v[166:169], v[230:233], v[88:91]
	v_mfma_f32_16x16x32_bf16 v[76:79], v[158:161], v[238:241], v[76:79]
	v_mfma_f32_16x16x32_bf16 v[72:75], v[166:169], v[238:241], v[72:75]
	s_setprio 0
	s_setprio 1
	v_mfma_f32_16x16x32_bf16 v[116:119], v[194:197], v[210:213], v[116:119]
	v_mfma_f32_16x16x32_bf16 v[112:115], v[202:205], v[210:213], v[112:115]
	v_mfma_f32_16x16x32_bf16 v[100:103], v[194:197], v[218:221], v[100:103]
	v_mfma_f32_16x16x32_bf16 v[96:99], v[202:205], v[218:221], v[96:99]
	v_mfma_f32_16x16x32_bf16 v[84:87], v[194:197], v[226:229], v[84:87]
	v_mfma_f32_16x16x32_bf16 v[80:83], v[202:205], v[226:229], v[80:83]
	v_mfma_f32_16x16x32_bf16 v[68:71], v[194:197], v[234:237], v[68:71]
	v_mfma_f32_16x16x32_bf16 v[64:67], v[202:205], v[234:237], v[64:67]
	v_mfma_f32_16x16x32_bf16 v[116:119], v[198:201], v[214:217], v[116:119]
	v_mfma_f32_16x16x32_bf16 v[112:115], v[206:209], v[214:217], v[112:115]
	v_mfma_f32_16x16x32_bf16 v[100:103], v[198:201], v[222:225], v[100:103]
	v_mfma_f32_16x16x32_bf16 v[96:99], v[206:209], v[222:225], v[96:99]
	v_mfma_f32_16x16x32_bf16 v[84:87], v[198:201], v[230:233], v[84:87]
	v_mfma_f32_16x16x32_bf16 v[80:83], v[206:209], v[230:233], v[80:83]
	v_mfma_f32_16x16x32_bf16 v[68:71], v[198:201], v[238:241], v[68:71]
	v_mfma_f32_16x16x32_bf16 v[64:67], v[206:209], v[238:241], v[64:67]
	s_setprio 0
	s_barrier
; #define PG8_STAGE(bufoff, gbase, voff) do { _Pragma("unroll") for (int _i = 0; _i < 2; ++_i) \
;         __builtin_amdgcn_global_load_lds((const unsigned*)((const char*)(gbase) + (voff)[_i]), (PG8_LAS unsigned*)(lds + (bufoff) + ldsw + _i * 8192), 16, 0, 0); } while (0)
; #define PG8_LDA(dst, b, h) do { _Pragma("unroll") for (int m = 0; m < 4; ++m) _Pragma("unroll") for (int k = 0; k < 2; ++k) dst[m][k] = *(const PG8_LAS bf16x8*)(lds + PG8_SA(b, h) + aoff + m * 2048 + k * 1024); } while (0)
; #define PG8_MMA(ai, bj, At, Bt) do { __builtin_amdgcn_s_setprio(1); _Pragma("unroll") for (int m = 0; m < 4; ++m) _Pragma("unroll") for (int n = 0; n < 2; ++n) _Pragma("unroll") for (int k = 0; k < 2; ++k) \
;         acc[ai][bj][m][n] = __builtin_amdgcn_mfma_f32_16x16x32_bf16(Bt[n][k], At[m][k], acc[ai][bj][m][n], 0, 0, 0); __builtin_amdgcn_s_setprio(0); } while (0)
; #define PG8_WAIT_V(n) asm volatile("s_waitcnt vmcnt(" #n ")" ::: "memory")
; #define PG8_WAIT_L(n) asm volatile("s_waitcnt lgkmcnt(" #n ")" ::: "memory")
; #define PG8_BAR __builtin_amdgcn_s_barrier()
; #define PG8_SCHED __builtin_amdgcn_sched_barrier(0)
; template <class Epi, class Sched, bool ALIGN_EPI = false, bool SP2 = false>
; __device__ __forceinline__ void gemm_phase(PG8_LAS unsigned char* lds, const Gemm g, const Sched& S, const Epi& E) {
;     ...
;             PG8_LDA(At, 1, 1); PG8_STAGE(PG8_SB(1, 0), b3, voffB); PG8_STAGE(PG8_SB(1, 1), b3 + hstep, voffB); PG8_STAGE(PG8_SA(1, 0), a3, voffA);
;             PG8_WAIT_V(8); PG8_WAIT_L(0); PG8_BAR; PG8_MMA(1, 0, At, B0); PG8_MMA(1, 1, At, B1); PG8_BAR; PG8_SCHED;
	s_add_i32 s24, s45, s29
	v_lshl_add_u64 v[170:171], v[170:171], 0, s[14:15]
	s_mov_b32 m0, s24
	ds_read_b128 v[210:213], v193 offset:49152
	ds_read_b128 v[214:217], v193 offset:50176
	ds_read_b128 v[218:221], v193 offset:51200
	ds_read_b128 v[222:225], v193 offset:52224
	ds_read_b128 v[226:229], v193 offset:53248
	ds_read_b128 v[230:233], v193 offset:54272
	ds_read_b128 v[234:237], v193 offset:55296
	ds_read_b128 v[238:241], v193 offset:56320
	global_load_lds_dwordx4 v[170:171], off
	s_add_i32 m0, s24, 0x2000
	s_add_u32 s24, s58, 0x40080
	v_lshl_add_u64 v[170:171], v[242:243], 0, s[14:15]
	s_addc_u32 s25, s59, 0
	s_add_i32 s45, s47, s29
	global_load_lds_dwordx4 v[170:171], off
	v_lshl_add_u64 v[170:171], s[24:25], 0, v[142:143]
	s_mov_b32 m0, s45
	s_nop 0
	global_load_lds_dwordx4 v[170:171], off
	v_lshl_add_u64 v[170:171], s[24:25], 0, v[146:147]
	s_add_i32 m0, s45, 0x2000
	s_nop 0
	global_load_lds_dwordx4 v[170:171], off
	v_lshl_add_u64 v[170:171], v[244:245], 0, s[14:15]
	s_mov_b32 m0, s90
	s_nop 0
	global_load_lds_dwordx4 v[170:171], off
	v_lshl_add_u64 v[170:171], v[246:247], 0, s[14:15]
	s_mov_b32 m0, s91
	s_nop 0
	global_load_lds_dwordx4 v[170:171], off
	s_waitcnt vmcnt(8)
	s_waitcnt lgkmcnt(0)
	s_barrier
	s_setprio 1
	s_waitcnt lgkmcnt(0)
	v_mfma_f32_16x16x32_bf16 v[60:63], v[128:131], v[210:213], v[60:63]
	v_mfma_f32_16x16x32_bf16 v[56:59], v[162:165], v[210:213], v[56:59]
	v_mfma_f32_16x16x32_bf16 v[44:47], v[128:131], v[218:221], v[44:47]
	v_mfma_f32_16x16x32_bf16 v[40:43], v[162:165], v[218:221], v[40:43]
	v_mfma_f32_16x16x32_bf16 v[28:31], v[128:131], v[226:229], v[28:31]
	v_mfma_f32_16x16x32_bf16 v[24:27], v[162:165], v[226:229], v[24:27]
	v_mfma_f32_16x16x32_bf16 v[12:15], v[128:131], v[234:237], v[12:15]
	v_mfma_f32_16x16x32_bf16 v[8:11], v[162:165], v[234:237], v[8:11]
	v_mfma_f32_16x16x32_bf16 v[60:63], v[158:161], v[214:217], v[60:63]
	v_mfma_f32_16x16x32_bf16 v[56:59], v[166:169], v[214:217], v[56:59]
	v_mfma_f32_16x16x32_bf16 v[44:47], v[158:161], v[222:225], v[44:47]
	v_mfma_f32_16x16x32_bf16 v[40:43], v[166:169], v[222:225], v[40:43]
	v_mfma_f32_16x16x32_bf16 v[28:31], v[158:161], v[230:233], v[28:31]
	v_mfma_f32_16x16x32_bf16 v[24:27], v[166:169], v[230:233], v[24:27]
	v_mfma_f32_16x16x32_bf16 v[12:15], v[158:161], v[238:241], v[12:15]
	v_mfma_f32_16x16x32_bf16 v[8:11], v[166:169], v[238:241], v[8:11]
	s_setprio 0
	s_setprio 1
	v_mfma_f32_16x16x32_bf16 v[52:55], v[194:197], v[210:213], v[52:55]
	v_mfma_f32_16x16x32_bf16 v[48:51], v[202:205], v[210:213], v[48:51]
	v_mfma_f32_16x16x32_bf16 v[36:39], v[194:197], v[218:221], v[36:39]
	v_mfma_f32_16x16x32_bf16 v[32:35], v[202:205], v[218:221], v[32:35]
	v_mfma_f32_16x16x32_bf16 v[20:23], v[194:197], v[226:229], v[20:23]
	v_mfma_f32_16x16x32_bf16 v[16:19], v[202:205], v[226:229], v[16:19]
	v_mfma_f32_16x16x32_bf16 v[4:7], v[194:197], v[234:237], v[4:7]
	v_mfma_f32_16x16x32_bf16 v[0:3], v[202:205], v[234:237], v[0:3]
	v_mfma_f32_16x16x32_bf16 v[52:55], v[198:201], v[214:217], v[52:55]
	v_mfma_f32_16x16x32_bf16 v[48:51], v[206:209], v[214:217], v[48:51]
	v_mfma_f32_16x16x32_bf16 v[36:39], v[198:201], v[222:225], v[36:39]
	v_mfma_f32_16x16x32_bf16 v[32:35], v[206:209], v[222:225], v[32:35]
	v_mfma_f32_16x16x32_bf16 v[20:23], v[198:201], v[230:233], v[20:23]
	v_mfma_f32_16x16x32_bf16 v[16:19], v[206:209], v[230:233], v[16:19]
	v_mfma_f32_16x16x32_bf16 v[4:7], v[198:201], v[238:241], v[4:7]
	v_mfma_f32_16x16x32_bf16 v[0:3], v[206:209], v[238:241], v[0:3]
	s_setprio 0
	s_barrier
	s_add_i32 s39, s39, 2
	s_add_u32 s56, s56, 0x100
	s_addc_u32 s57, s57, 0
	s_add_u32 s33, s33, 0x100
	s_addc_u32 s37, s37, 0
	s_cmp_gt_u32 s39, 13

; #define PG8_STAGE(bufoff, gbase, voff) do { _Pragma("unroll") for (int _i = 0; _i < 2; ++_i) \
;         __builtin_amdgcn_global_load_lds((const unsigned*)((const char*)(gbase) + (voff)[_i]), (PG8_LAS unsigned*)(lds + (bufoff) + ldsw + _i * 8192), 16, 0, 0); } while (0)
; #define PG8_WAIT_V(n) asm volatile("s_waitcnt vmcnt(" #n ")" ::: "memory")
; #define PG8_BAR __builtin_amdgcn_s_barrier()
; template <class Epi, class Sched, bool ALIGN_EPI = false, bool SP2 = false>
; __device__ __forceinline__ void gemm_phase(PG8_LAS unsigned char* lds, const Gemm g, const Sched& S, const Epi& E) {
;     ...
;     for (int i = 0; i < 2; ++i) { int R, C; stage_rc(tid * 16 + i * 8192, R, C); const int Rb = Epi::PERM ? ((R & ~31) + perm32(R & 31)) : R;
;         voffA[i] = (unsigned)(R * K + C) * 2u; voffB[i] = (unsigned)(Rb * K + C) * 2u; }
;     const size_t kstep = (size_t)(BK * 2);
;     const size_t hstep = (size_t)HALF * K * 2;
;     const size_t tstep = 2 * hstep;
;     const unsigned ldsw = (unsigned)wid * 1024u;
;     const int aoff = lds_byte(wr * 64 + fr, fq * 8), boff = lds_byte(wc * 32 + fr, fq * 8);
;     ...
;         PG8_WAIT_V(2); PG8_BAR;
;         PG8_STAGE(PG8_SB(1, 0), cB + kstep, voffB); PG8_STAGE(PG8_SA(1, 0), cA + kstep, voffA); PG8_STAGE(PG8_SB(1, 1), cB + hstep + kstep, voffB);
;         PG8_WAIT_V(6); PG8_BAR;
.LBB0_544:
	s_lshl_b32 s8, s8, 5
	s_and_b32 s17, s8, 0x60
	s_add_i32 m0, s29, 0x18000
	v_lshl_add_u64 v[6:7], v[6:7], 0, s[14:15]
	s_lshl_b32 s16, s1, 13
	s_lshl_b32 s20, s17, 7
	s_waitcnt vmcnt(2)
	s_barrier
	global_load_lds_dwordx4 v[6:7], off
	v_lshl_add_u64 v[4:5], v[4:5], 0, s[14:15]
	s_add_i32 m0, s29, 0x1a000
	s_add_i32 s65, s29, 0x8000
	s_add_i32 s66, s29, 0xa000
	global_load_lds_dwordx4 v[4:5], off
	v_lshl_add_u64 v[0:1], v[0:1], 0, s[14:15]
	s_mov_b32 m0, s65
	s_add_u32 s8, s58, 0x40080
	global_load_lds_dwordx4 v[0:1], off
	v_lshl_add_u64 v[0:1], v[2:3], 0, s[14:15]
	s_mov_b32 m0, s66
	s_addc_u32 s9, s59, 0
	global_load_lds_dwordx4 v[0:1], off
	s_add_i32 m0, s29, 0x1c000
	v_lshl_add_u64 v[0:1], s[8:9], 0, v[132:133]
	global_load_lds_dwordx4 v[0:1], off
	v_lshl_add_u64 v[0:1], s[8:9], 0, v[140:141]
	s_add_i32 m0, s29, 0x1e000
	s_cmpk_lt_u32 s0, 0x100
	global_load_lds_dwordx4 v[0:1], off
	v_bfe_u32 v1, v8, 4, 2
	v_and_b32_e32 v0, 15, v8
	v_lshlrev_b32_e32 v2, 4, v1
	v_lshl_or_b32 v158, s1, 6, v0
	v_lshl_or_b32 v0, v0, 6, v2
	v_lshlrev_b32_e32 v2, 2, v8
	v_and_b32_e32 v2, 32, v2
	v_bitop3_b32 v3, v0, s16, v2 bitop3:0xde
	v_bitop3_b32 v159, v0, s20, v2 bitop3:0xde
	v_lshlrev_b32_e32 v0, 14, v9
	v_and_b32_e32 v0, 0xffff8000, v0
	v_cmp_eq_u32_e64 s[40:41], 0, v1
	v_lshl_or_b32 v160, v1, 3, s17
	v_lshl_add_u32 v0, v10, 11, v0
	v_and_b32_e32 v1, 1, v9
	v_lshl_or_b32 v0, v1, 6, v0
	v_lshl_add_u32 v142, v11, 1, v0
	v_lshlrev_b32_e32 v0, 14, v12
	v_and_b32_e32 v0, 0xffff8000, v0
	s_waitcnt vmcnt(0)
	v_lshl_add_u32 v0, v13, 11, v0
	v_and_b32_e32 v1, 1, v12
	v_lshl_or_b32 v0, v1, 6, v0
	s_cselect_b64 s[8:9], -1, 0
	s_mov_b32 s67, 0
	s_ashr_i32 s68, s83, 31
	s_ashr_i32 s69, s84, 31
	v_mov_b32_e32 v143, v133
	v_lshl_add_u32 v144, v14, 1, v0
	v_mov_b32_e32 v145, v133
	v_add_u32_e32 v161, 0, v3
	s_barrier
	s_branch .LBB0_547

; #define PG8_STAGE(bufoff, gbase, voff) do { _Pragma("unroll") for (int _i = 0; _i < 2; ++_i) \
;         __builtin_amdgcn_global_load_lds((const unsigned*)((const char*)(gbase) + (voff)[_i]), (PG8_LAS unsigned*)(lds + (bufoff) + ldsw + _i * 8192), 16, 0, 0); } while (0)
; #define PG8_LDA(dst, b, h) do { _Pragma("unroll") for (int m = 0; m < 4; ++m) _Pragma("unroll") for (int k = 0; k < 2; ++k) dst[m][k] = *(const PG8_LAS bf16x8*)(lds + PG8_SA(b, h) + aoff + m * 2048 + k * 1024); } while (0)
; #define PG8_LDB(dst, b, h) do { _Pragma("unroll") for (int n = 0; n < 2; ++n) _Pragma("unroll") for (int k = 0; k < 2; ++k) dst[n][k] = *(const PG8_LAS bf16x8*)(lds + PG8_SB(b, h) + boff + n * 2048 + k * 1024); } while (0)
; #define PG8_WAIT_V(n) asm volatile("s_waitcnt vmcnt(" #n ")" ::: "memory")
; #define PG8_WAIT_L(n) asm volatile("s_waitcnt lgkmcnt(" #n ")" ::: "memory")
; #define PG8_BAR __builtin_amdgcn_s_barrier()
; #define PG8_SCHED __builtin_amdgcn_sched_barrier(0)
; template <class Epi, class Sched, bool ALIGN_EPI = false, bool SP2 = false>
; __device__ __forceinline__ void gemm_phase(PG8_LAS unsigned char* lds, const Gemm g, const Sched& S, const Epi& E) {
;     ...
;         const char* nA = has_next ? (const char*)g.A + (size_t)nxt.pm * tstep : cA; const char* nB = has_next ? (const char*)g.Bt + (size_t)nxt.pn * tstep : cB;
;         for (int t = 0; t < nt; t += 2) {
;             const bool last = (t == nt - 2);
;             const char* a1 = cA + (size_t)(t + 1) * kstep;
;             const char* a2 = last ? nA : cA + (size_t)(t + 2) * kstep; const char* b2 = last ? nB : cB + (size_t)(t + 2) * kstep;
;             const char* a3 = a2 + kstep; const char* b3 = b2 + kstep;
;             if (last && has_next) S.a_ready(nxt);
;             if constexpr (SP2) {
;             PG8_LDB(B0, 0, 0); PG8_LDB(B1, 0, 1); PG8_SCHED; PG8_LDA(At, 0, 0); PG8_STAGE(PG8_SA(1, 1), a1 + hstep, voffA);
;             PG8_WAIT_V(8); PG8_WAIT_L(0); PG8_BAR; PG8_MMA(0, 0, At, B0); PG8_MMA(0, 1, At, B1); PG8_BAR; PG8_SCHED;
;             PG8_LDA(At, 0, 1); PG8_STAGE(PG8_SB(0, 0), b2, voffB); PG8_STAGE(PG8_SB(0, 1), b2 + hstep, voffB); PG8_STAGE(PG8_SA(0, 0), a2, voffA);
;             PG8_WAIT_V(8); PG8_WAIT_L(0); PG8_BAR; PG8_MMA(1, 0, At, B0); PG8_MMA(1, 1, At, B1); PG8_BAR; PG8_SCHED;
.LBB0_553:
	s_ashr_i32 s21, s20, 31
	s_lshl_b64 s[0:1], s[20:21], 19
	s_add_u32 s38, s26, s0
	s_addc_u32 s39, s27, s1
	s_and_b64 s[0:1], s[42:43], exec
	s_cselect_b32 s0, s39, s57
	s_cselect_b32 s1, s38, s56
	s_ashr_i32 s17, s16, 31
	s_lshl_b64 s[24:25], s[16:17], 19
	s_add_u32 s48, s10, s24
	s_addc_u32 s49, s12, s25
	s_and_b64 s[24:25], s[42:43], exec
	s_cselect_b32 s17, s49, s59
	s_cselect_b32 s21, s48, s58
	s_add_u32 s56, s56, 0x40080
	s_addc_u32 s57, s57, 0
	s_add_u32 s22, s58, 0x100
	s_addc_u32 s33, s59, 0
	s_mov_b32 s45, -2
	s_add_u32 s24, s56, 0xfffc0080
	s_addc_u32 s25, s57, -1
	s_add_i32 s47, 0, 0x10000
	s_cmp_eq_u32 s45, 12
	s_cselect_b32 s61, s0, s25
	s_cselect_b32 s60, s1, s24
	s_cselect_b32 s59, s17, s33
	s_cselect_b32 s58, s21, s22
	s_add_i32 s50, 0, 0x14000
	v_add_u32_e32 v162, s47, v159
	v_add_u32_e32 v170, s50, v159
	ds_read_b128 v[146:149], v162
	ds_read_b128 v[150:153], v162 offset:1024
	ds_read_b128 v[154:157], v162 offset:2048
	ds_read_b128 v[162:165], v162 offset:3072
	ds_read_b128 v[166:169], v170
	ds_read_b128 v[192:195], v170 offset:1024
	ds_read_b128 v[196:199], v170 offset:2048
	ds_read_b128 v[200:203], v170 offset:3072
	v_lshl_add_u64 v[170:171], s[56:57], 0, v[142:143]
	s_add_i32 m0, s29, 0xc000
	ds_read_b128 v[204:207], v161
	ds_read_b128 v[208:211], v161 offset:1024
	ds_read_b128 v[212:215], v161 offset:2048
	ds_read_b128 v[216:219], v161 offset:3072
	ds_read_b128 v[220:223], v161 offset:4096
	ds_read_b128 v[224:227], v161 offset:5120
	ds_read_b128 v[228:231], v161 offset:6144
	ds_read_b128 v[232:235], v161 offset:7168
	global_load_lds_dwordx4 v[170:171], off
	v_lshl_add_u64 v[170:171], s[56:57], 0, v[144:145]
	s_add_i32 m0, s29, 0xe000
	s_nop 0
	global_load_lds_dwordx4 v[170:171], off
	s_waitcnt vmcnt(12)
	s_waitcnt lgkmcnt(0)
	s_barrier
	s_setprio 1
	s_waitcnt lgkmcnt(0)
	v_mfma_f32_16x16x32_bf16 v[124:127], v[146:149], v[204:207], 0
	v_mfma_f32_16x16x32_bf16 v[120:123], v[154:157], v[204:207], 0
	v_mfma_f32_16x16x32_bf16 v[108:111], v[146:149], v[212:215], 0
	v_mfma_f32_16x16x32_bf16 v[104:107], v[154:157], v[212:215], 0
	v_mfma_f32_16x16x32_bf16 v[92:95], v[146:149], v[220:223], 0
	v_mfma_f32_16x16x32_bf16 v[88:91], v[154:157], v[220:223], 0
	v_mfma_f32_16x16x32_bf16 v[76:79], v[146:149], v[228:231], 0
	v_mfma_f32_16x16x32_bf16 v[72:75], v[154:157], v[228:231], 0
	v_mfma_f32_16x16x32_bf16 v[124:127], v[150:153], v[208:211], v[124:127]
	v_mfma_f32_16x16x32_bf16 v[120:123], v[162:165], v[208:211], v[120:123]
	v_mfma_f32_16x16x32_bf16 v[108:111], v[150:153], v[216:219], v[108:111]
	v_mfma_f32_16x16x32_bf16 v[104:107], v[162:165], v[216:219], v[104:107]
	v_mfma_f32_16x16x32_bf16 v[92:95], v[150:153], v[224:227], v[92:95]
	v_mfma_f32_16x16x32_bf16 v[88:91], v[162:165], v[224:227], v[88:91]
	v_mfma_f32_16x16x32_bf16 v[76:79], v[150:153], v[232:235], v[76:79]
	v_mfma_f32_16x16x32_bf16 v[72:75], v[162:165], v[232:235], v[72:75]
	s_setprio 0
	s_setprio 1
	v_mfma_f32_16x16x32_bf16 v[116:119], v[166:169], v[204:207], 0
	v_mfma_f32_16x16x32_bf16 v[112:115], v[196:199], v[204:207], 0
	v_mfma_f32_16x16x32_bf16 v[100:103], v[166:169], v[212:215], 0
	v_mfma_f32_16x16x32_bf16 v[96:99], v[196:199], v[212:215], 0
	v_mfma_f32_16x16x32_bf16 v[84:87], v[166:169], v[220:223], 0
	v_mfma_f32_16x16x32_bf16 v[80:83], v[196:199], v[220:223], 0
	v_mfma_f32_16x16x32_bf16 v[68:71], v[166:169], v[228:231], 0
	v_mfma_f32_16x16x32_bf16 v[64:67], v[196:199], v[228:231], 0
	v_mfma_f32_16x16x32_bf16 v[116:119], v[192:195], v[208:211], v[116:119]
	v_mfma_f32_16x16x32_bf16 v[112:115], v[200:203], v[208:211], v[112:115]
	v_mfma_f32_16x16x32_bf16 v[100:103], v[192:195], v[216:219], v[100:103]
	v_mfma_f32_16x16x32_bf16 v[96:99], v[200:203], v[216:219], v[96:99]
	v_mfma_f32_16x16x32_bf16 v[84:87], v[192:195], v[224:227], v[84:87]
	v_mfma_f32_16x16x32_bf16 v[80:83], v[200:203], v[224:227], v[80:83]
	v_mfma_f32_16x16x32_bf16 v[68:71], v[192:195], v[232:235], v[68:71]
	v_mfma_f32_16x16x32_bf16 v[64:67], v[200:203], v[232:235], v[64:67]
	s_setprio 0
	s_barrier
	s_add_i32 s24, s47, s23
	v_lshl_add_u64 v[170:171], s[58:59], 0, v[132:133]
	s_mov_b32 m0, s24
	ds_read_b128 v[204:207], v161 offset:16384
	ds_read_b128 v[208:211], v161 offset:17408
	ds_read_b128 v[212:215], v161 offset:18432
	ds_read_b128 v[216:219], v161 offset:19456
	ds_read_b128 v[220:223], v161 offset:20480
	ds_read_b128 v[224:227], v161 offset:21504
	ds_read_b128 v[228:231], v161 offset:22528
	ds_read_b128 v[232:235], v161 offset:23552
	global_load_lds_dwordx4 v[170:171], off
	s_add_i32 m0, s24, 0x2000
	s_add_u32 s24, s58, 0x40000
	v_lshl_add_u64 v[236:237], s[58:59], 0, v[140:141]
	s_addc_u32 s25, s59, 0
	s_add_i32 s47, s50, s23
	global_load_lds_dwordx4 v[236:237], off
	v_lshl_add_u64 v[238:239], s[24:25], 0, v[132:133]
	s_mov_b32 m0, s47
	v_lshl_add_u64 v[240:241], s[60:61], 0, v[130:131]
	global_load_lds_dwordx4 v[238:239], off
	v_lshl_add_u64 v[238:239], s[24:25], 0, v[140:141]
	s_add_i32 m0, s47, 0x2000
	s_nop 0
	global_load_lds_dwordx4 v[238:239], off
	v_lshl_add_u64 v[238:239], s[60:61], 0, v[128:129]
	s_mov_b32 m0, s29
	s_nop 0
	global_load_lds_dwordx4 v[238:239], off
	s_mov_b32 m0, s62
	s_nop 0
	global_load_lds_dwordx4 v[240:241], off
	s_waitcnt vmcnt(18)
	s_waitcnt lgkmcnt(0)
	s_barrier
; #define PG8_STAGE(bufoff, gbase, voff) do { _Pragma("unroll") for (int _i = 0; _i < 2; ++_i) \
;         __builtin_amdgcn_global_load_lds((const unsigned*)((const char*)(gbase) + (voff)[_i]), (PG8_LAS unsigned*)(lds + (bufoff) + ldsw + _i * 8192), 16, 0, 0); } while (0)
; #define PG8_LDA(dst, b, h) do { _Pragma("unroll") for (int m = 0; m < 4; ++m) _Pragma("unroll") for (int k = 0; k < 2; ++k) dst[m][k] = *(const PG8_LAS bf16x8*)(lds + PG8_SA(b, h) + aoff + m * 2048 + k * 1024); } while (0)
; #define PG8_LDB(dst, b, h) do { _Pragma("unroll") for (int n = 0; n < 2; ++n) _Pragma("unroll") for (int k = 0; k < 2; ++k) dst[n][k] = *(const PG8_LAS bf16x8*)(lds + PG8_SB(b, h) + boff + n * 2048 + k * 1024); } while (0)
; #define PG8_MMA(ai, bj, At, Bt) do { __builtin_amdgcn_s_setprio(1); _Pragma("unroll") for (int m = 0; m < 4; ++m) _Pragma("unroll") for (int n = 0; n < 2; ++n) _Pragma("unroll") for (int k = 0; k < 2; ++k) \
;         acc[ai][bj][m][n] = __builtin_amdgcn_mfma_f32_16x16x32_bf16(Bt[n][k], At[m][k], acc[ai][bj][m][n], 0, 0, 0); __builtin_amdgcn_s_setprio(0); } while (0)
; #define PG8_WAIT_V(n) asm volatile("s_waitcnt vmcnt(" #n ")" ::: "memory")
; #define PG8_WAIT_L(n) asm volatile("s_waitcnt lgkmcnt(" #n ")" ::: "memory")
; #define PG8_BAR __builtin_amdgcn_s_barrier()
; #define PG8_SCHED __builtin_amdgcn_sched_barrier(0)
; template <class Epi, class Sched, bool ALIGN_EPI = false, bool SP2 = false>
; __device__ __forceinline__ void gemm_phase(PG8_LAS unsigned char* lds, const Gemm g, const Sched& S, const Epi& E) {
;     ...
;             PG8_WAIT_V(8); PG8_WAIT_L(0); PG8_BAR; PG8_MMA(1, 0, At, B0); PG8_MMA(1, 1, At, B1); PG8_BAR; PG8_SCHED;
;             PG8_LDB(B0, 1, 0); PG8_LDB(B1, 1, 1); PG8_SCHED; PG8_LDA(At, 1, 0); PG8_STAGE(PG8_SA(0, 1), a2 + hstep, voffA);
;             PG8_WAIT_V(8); PG8_WAIT_L(0); PG8_BAR; PG8_MMA(0, 0, At, B0); PG8_MMA(0, 1, At, B1); PG8_BAR; PG8_SCHED;
	s_setprio 1
	s_waitcnt lgkmcnt(0)
	v_mfma_f32_16x16x32_bf16 v[60:63], v[146:149], v[204:207], 0
	v_mfma_f32_16x16x32_bf16 v[56:59], v[154:157], v[204:207], 0
	v_mfma_f32_16x16x32_bf16 v[44:47], v[146:149], v[212:215], 0
	v_mfma_f32_16x16x32_bf16 v[40:43], v[154:157], v[212:215], 0
	v_mfma_f32_16x16x32_bf16 v[28:31], v[146:149], v[220:223], 0
	v_mfma_f32_16x16x32_bf16 v[24:27], v[154:157], v[220:223], 0
	v_mfma_f32_16x16x32_bf16 v[12:15], v[146:149], v[228:231], 0
	v_mfma_f32_16x16x32_bf16 v[8:11], v[154:157], v[228:231], 0
	v_mfma_f32_16x16x32_bf16 v[60:63], v[150:153], v[208:211], v[60:63]
	v_mfma_f32_16x16x32_bf16 v[56:59], v[162:165], v[208:211], v[56:59]
	v_mfma_f32_16x16x32_bf16 v[44:47], v[150:153], v[216:219], v[44:47]
	v_mfma_f32_16x16x32_bf16 v[40:43], v[162:165], v[216:219], v[40:43]
	v_mfma_f32_16x16x32_bf16 v[28:31], v[150:153], v[224:227], v[28:31]
	v_mfma_f32_16x16x32_bf16 v[24:27], v[162:165], v[224:227], v[24:27]
	v_mfma_f32_16x16x32_bf16 v[12:15], v[150:153], v[232:235], v[12:15]
	v_mfma_f32_16x16x32_bf16 v[8:11], v[162:165], v[232:235], v[8:11]
	s_setprio 0
	s_setprio 1
	v_mfma_f32_16x16x32_bf16 v[52:55], v[166:169], v[204:207], 0
	v_mfma_f32_16x16x32_bf16 v[48:51], v[196:199], v[204:207], 0
	v_mfma_f32_16x16x32_bf16 v[36:39], v[166:169], v[212:215], 0
	v_mfma_f32_16x16x32_bf16 v[32:35], v[196:199], v[212:215], 0
	v_mfma_f32_16x16x32_bf16 v[20:23], v[166:169], v[220:223], 0
	v_mfma_f32_16x16x32_bf16 v[16:19], v[196:199], v[220:223], 0
	v_mfma_f32_16x16x32_bf16 v[4:7], v[166:169], v[228:231], 0
	v_mfma_f32_16x16x32_bf16 v[0:3], v[196:199], v[228:231], 0
	v_mfma_f32_16x16x32_bf16 v[52:55], v[192:195], v[208:211], v[52:55]
	v_mfma_f32_16x16x32_bf16 v[48:51], v[200:203], v[208:211], v[48:51]
	v_mfma_f32_16x16x32_bf16 v[36:39], v[192:195], v[216:219], v[36:39]
	v_mfma_f32_16x16x32_bf16 v[32:35], v[200:203], v[216:219], v[32:35]
	v_mfma_f32_16x16x32_bf16 v[20:23], v[192:195], v[224:227], v[20:23]
	v_mfma_f32_16x16x32_bf16 v[16:19], v[200:203], v[224:227], v[16:19]
	v_mfma_f32_16x16x32_bf16 v[4:7], v[192:195], v[232:235], v[4:7]
	v_mfma_f32_16x16x32_bf16 v[0:3], v[200:203], v[232:235], v[0:3]
	s_setprio 0
	s_barrier
	s_add_i32 s47, 0, 0x18000
	s_add_i32 s50, 0, 0x1c000
	v_add_u32_e32 v162, s47, v159
	v_add_u32_e32 v184, s50, v159
	ds_read_b128 v[146:149], v162
	ds_read_b128 v[150:153], v162 offset:1024
	ds_read_b128 v[154:157], v162 offset:2048
	ds_read_b128 v[162:165], v162 offset:3072
	ds_read_b128 v[166:169], v184
	ds_read_b128 v[192:195], v184 offset:1024
	ds_read_b128 v[196:199], v184 offset:2048
	ds_read_b128 v[200:203], v184 offset:3072
	s_add_u32 s24, s60, 0x40000
	s_addc_u32 s25, s61, 0
	s_mov_b32 m0, s63
	v_lshl_add_u64 v[242:243], s[24:25], 0, v[128:129]
	ds_read_b128 v[204:207], v161 offset:32768
	ds_read_b128 v[208:211], v161 offset:33792
	ds_read_b128 v[212:215], v161 offset:34816
	ds_read_b128 v[216:219], v161 offset:35840
	ds_read_b128 v[220:223], v161 offset:36864
	ds_read_b128 v[224:227], v161 offset:37888
	ds_read_b128 v[228:231], v161 offset:38912
	ds_read_b128 v[232:235], v161 offset:39936
	global_load_lds_dwordx4 v[242:243], off
	v_lshl_add_u64 v[242:243], s[24:25], 0, v[130:131]
	s_mov_b32 m0, s64
	s_nop 0
	global_load_lds_dwordx4 v[242:243], off
	s_waitcnt vmcnt(8)
	s_waitcnt lgkmcnt(0)
	s_barrier
	s_setprio 1
	s_waitcnt lgkmcnt(0)
	v_mfma_f32_16x16x32_bf16 v[124:127], v[146:149], v[204:207], v[124:127]
	v_mfma_f32_16x16x32_bf16 v[120:123], v[154:157], v[204:207], v[120:123]
	v_mfma_f32_16x16x32_bf16 v[108:111], v[146:149], v[212:215], v[108:111]
	v_mfma_f32_16x16x32_bf16 v[104:107], v[154:157], v[212:215], v[104:107]
	v_mfma_f32_16x16x32_bf16 v[92:95], v[146:149], v[220:223], v[92:95]
	v_mfma_f32_16x16x32_bf16 v[88:91], v[154:157], v[220:223], v[88:91]
	v_mfma_f32_16x16x32_bf16 v[76:79], v[146:149], v[228:231], v[76:79]
	v_mfma_f32_16x16x32_bf16 v[72:75], v[154:157], v[228:231], v[72:75]
	v_mfma_f32_16x16x32_bf16 v[124:127], v[150:153], v[208:211], v[124:127]
	v_mfma_f32_16x16x32_bf16 v[120:123], v[162:165], v[208:211], v[120:123]
	v_mfma_f32_16x16x32_bf16 v[108:111], v[150:153], v[216:219], v[108:111]
	v_mfma_f32_16x16x32_bf16 v[104:107], v[162:165], v[216:219], v[104:107]
	v_mfma_f32_16x16x32_bf16 v[92:95], v[150:153], v[224:227], v[92:95]
	v_mfma_f32_16x16x32_bf16 v[88:91], v[162:165], v[224:227], v[88:91]
	v_mfma_f32_16x16x32_bf16 v[76:79], v[150:153], v[232:235], v[76:79]
	v_mfma_f32_16x16x32_bf16 v[72:75], v[162:165], v[232:235], v[72:75]
	s_setprio 0
	s_setprio 1
	v_mfma_f32_16x16x32_bf16 v[116:119], v[166:169], v[204:207], v[116:119]
	v_mfma_f32_16x16x32_bf16 v[112:115], v[196:199], v[204:207], v[112:115]
	v_mfma_f32_16x16x32_bf16 v[100:103], v[166:169], v[212:215], v[100:103]
	v_mfma_f32_16x16x32_bf16 v[96:99], v[196:199], v[212:215], v[96:99]
	v_mfma_f32_16x16x32_bf16 v[84:87], v[166:169], v[220:223], v[84:87]
	v_mfma_f32_16x16x32_bf16 v[80:83], v[196:199], v[220:223], v[80:83]
	v_mfma_f32_16x16x32_bf16 v[68:71], v[166:169], v[228:231], v[68:71]
	v_mfma_f32_16x16x32_bf16 v[64:67], v[196:199], v[228:231], v[64:67]
	v_mfma_f32_16x16x32_bf16 v[116:119], v[192:195], v[208:211], v[116:119]
	v_mfma_f32_16x16x32_bf16 v[112:115], v[200:203], v[208:211], v[112:115]
	v_mfma_f32_16x16x32_bf16 v[100:103], v[192:195], v[216:219], v[100:103]
	v_mfma_f32_16x16x32_bf16 v[96:99], v[200:203], v[216:219], v[96:99]
	v_mfma_f32_16x16x32_bf16 v[84:87], v[192:195], v[224:227], v[84:87]
	v_mfma_f32_16x16x32_bf16 v[80:83], v[200:203], v[224:227], v[80:83]
	v_mfma_f32_16x16x32_bf16 v[68:71], v[192:195], v[232:235], v[68:71]
	v_mfma_f32_16x16x32_bf16 v[64:67], v[200:203], v[232:235], v[64:67]
	s_setprio 0
	s_barrier
; #define PG8_STAGE(bufoff, gbase, voff) do { _Pragma("unroll") for (int _i = 0; _i < 2; ++_i) \
;         __builtin_amdgcn_global_load_lds((const unsigned*)((const char*)(gbase) + (voff)[_i]), (PG8_LAS unsigned*)(lds + (bufoff) + ldsw + _i * 8192), 16, 0, 0); } while (0)
; #define PG8_LDA(dst, b, h) do { _Pragma("unroll") for (int m = 0; m < 4; ++m) _Pragma("unroll") for (int k = 0; k < 2; ++k) dst[m][k] = *(const PG8_LAS bf16x8*)(lds + PG8_SA(b, h) + aoff + m * 2048 + k * 1024); } while (0)
; #define PG8_MMA(ai, bj, At, Bt) do { __builtin_amdgcn_s_setprio(1); _Pragma("unroll") for (int m = 0; m < 4; ++m) _Pragma("unroll") for (int n = 0; n < 2; ++n) _Pragma("unroll") for (int k = 0; k < 2; ++k) \
;         acc[ai][bj][m][n] = __builtin_amdgcn_mfma_f32_16x16x32_bf16(Bt[n][k], At[m][k], acc[ai][bj][m][n], 0, 0, 0); __builtin_amdgcn_s_setprio(0); } while (0)
; #define PG8_WAIT_V(n) asm volatile("s_waitcnt vmcnt(" #n ")" ::: "memory")
; #define PG8_WAIT_L(n) asm volatile("s_waitcnt lgkmcnt(" #n ")" ::: "memory")
; #define PG8_BAR __builtin_amdgcn_s_barrier()
; #define PG8_SCHED __builtin_amdgcn_sched_barrier(0)
; template <class Epi, class Sched, bool ALIGN_EPI = false, bool SP2 = false>
; __device__ __forceinline__ void gemm_phase(PG8_LAS unsigned char* lds, const Gemm g, const Sched& S, const Epi& E) {
;     ...
;             PG8_LDA(At, 1, 1); PG8_STAGE(PG8_SB(1, 0), b3, voffB); PG8_STAGE(PG8_SB(1, 1), b3 + hstep, voffB); PG8_STAGE(PG8_SA(1, 0), a3, voffA);
;             PG8_WAIT_V(8); PG8_WAIT_L(0); PG8_BAR; PG8_MMA(1, 0, At, B0); PG8_MMA(1, 1, At, B1); PG8_BAR; PG8_SCHED;
	s_add_i32 s24, s47, s23
	v_lshl_add_u64 v[170:171], v[170:171], 0, s[14:15]
	s_mov_b32 m0, s24
	ds_read_b128 v[204:207], v161 offset:49152
	ds_read_b128 v[208:211], v161 offset:50176
	ds_read_b128 v[212:215], v161 offset:51200
	ds_read_b128 v[216:219], v161 offset:52224
	ds_read_b128 v[220:223], v161 offset:53248
	ds_read_b128 v[224:227], v161 offset:54272
	ds_read_b128 v[228:231], v161 offset:55296
	ds_read_b128 v[232:235], v161 offset:56320
	global_load_lds_dwordx4 v[170:171], off
	s_add_i32 m0, s24, 0x2000
	s_add_u32 s24, s58, 0x40080
	v_lshl_add_u64 v[170:171], v[236:237], 0, s[14:15]
	s_addc_u32 s25, s59, 0
	s_add_i32 s47, s50, s23
	global_load_lds_dwordx4 v[170:171], off
	v_lshl_add_u64 v[170:171], s[24:25], 0, v[132:133]
	s_mov_b32 m0, s47
	s_nop 0
	global_load_lds_dwordx4 v[170:171], off
	v_lshl_add_u64 v[170:171], s[24:25], 0, v[140:141]
	s_add_i32 m0, s47, 0x2000
	s_nop 0
	global_load_lds_dwordx4 v[170:171], off
	v_lshl_add_u64 v[170:171], v[238:239], 0, s[14:15]
	s_mov_b32 m0, s65
	s_nop 0
	global_load_lds_dwordx4 v[170:171], off
	v_lshl_add_u64 v[170:171], v[240:241], 0, s[14:15]
	s_mov_b32 m0, s66
	s_nop 0
	global_load_lds_dwordx4 v[170:171], off
	s_waitcnt vmcnt(8)
	s_waitcnt lgkmcnt(0)
	s_barrier
	s_setprio 1
	s_waitcnt lgkmcnt(0)
	v_mfma_f32_16x16x32_bf16 v[60:63], v[146:149], v[204:207], v[60:63]
	v_mfma_f32_16x16x32_bf16 v[56:59], v[154:157], v[204:207], v[56:59]
	v_mfma_f32_16x16x32_bf16 v[44:47], v[146:149], v[212:215], v[44:47]
	v_mfma_f32_16x16x32_bf16 v[40:43], v[154:157], v[212:215], v[40:43]
	v_mfma_f32_16x16x32_bf16 v[28:31], v[146:149], v[220:223], v[28:31]
	v_mfma_f32_16x16x32_bf16 v[24:27], v[154:157], v[220:223], v[24:27]
	v_mfma_f32_16x16x32_bf16 v[12:15], v[146:149], v[228:231], v[12:15]
	v_mfma_f32_16x16x32_bf16 v[8:11], v[154:157], v[228:231], v[8:11]
	v_mfma_f32_16x16x32_bf16 v[60:63], v[150:153], v[208:211], v[60:63]
	v_mfma_f32_16x16x32_bf16 v[56:59], v[162:165], v[208:211], v[56:59]
	v_mfma_f32_16x16x32_bf16 v[44:47], v[150:153], v[216:219], v[44:47]
	v_mfma_f32_16x16x32_bf16 v[40:43], v[162:165], v[216:219], v[40:43]
	v_mfma_f32_16x16x32_bf16 v[28:31], v[150:153], v[224:227], v[28:31]
	v_mfma_f32_16x16x32_bf16 v[24:27], v[162:165], v[224:227], v[24:27]
	v_mfma_f32_16x16x32_bf16 v[12:15], v[150:153], v[232:235], v[12:15]
	v_mfma_f32_16x16x32_bf16 v[8:11], v[162:165], v[232:235], v[8:11]
	s_setprio 0
	s_setprio 1
	v_mfma_f32_16x16x32_bf16 v[52:55], v[166:169], v[204:207], v[52:55]
	v_mfma_f32_16x16x32_bf16 v[48:51], v[196:199], v[204:207], v[48:51]
	v_mfma_f32_16x16x32_bf16 v[36:39], v[166:169], v[212:215], v[36:39]
	v_mfma_f32_16x16x32_bf16 v[32:35], v[196:199], v[212:215], v[32:35]
	v_mfma_f32_16x16x32_bf16 v[20:23], v[166:169], v[220:223], v[20:23]
	v_mfma_f32_16x16x32_bf16 v[16:19], v[196:199], v[220:223], v[16:19]
	v_mfma_f32_16x16x32_bf16 v[4:7], v[166:169], v[228:231], v[4:7]
	v_mfma_f32_16x16x32_bf16 v[0:3], v[196:199], v[228:231], v[0:3]
	v_mfma_f32_16x16x32_bf16 v[52:55], v[192:195], v[208:211], v[52:55]
	v_mfma_f32_16x16x32_bf16 v[48:51], v[200:203], v[208:211], v[48:51]
	v_mfma_f32_16x16x32_bf16 v[36:39], v[192:195], v[216:219], v[36:39]
	v_mfma_f32_16x16x32_bf16 v[32:35], v[200:203], v[216:219], v[32:35]
	v_mfma_f32_16x16x32_bf16 v[20:23], v[192:195], v[224:227], v[20:23]
	v_mfma_f32_16x16x32_bf16 v[16:19], v[200:203], v[224:227], v[16:19]
	v_mfma_f32_16x16x32_bf16 v[4:7], v[192:195], v[232:235], v[4:7]
	v_mfma_f32_16x16x32_bf16 v[0:3], v[200:203], v[232:235], v[0:3]
	s_setprio 0
	s_barrier
	s_add_i32 s45, s45, 2
	s_add_u32 s56, s56, 0x100
	s_addc_u32 s57, s57, 0
	s_add_u32 s22, s22, 0x100
	s_addc_u32 s33, s33, 0
	s_cmp_gt_u32 s45, 13

; #define PG8_STAGE(bufoff, gbase, voff) do { _Pragma("unroll") for (int _i = 0; _i < 2; ++_i) \
;         __builtin_amdgcn_global_load_lds((const unsigned*)((const char*)(gbase) + (voff)[_i]), (PG8_LAS unsigned*)(lds + (bufoff) + ldsw + _i * 8192), 16, 0, 0); } while (0)
; #define PG8_WAIT_V(n) asm volatile("s_waitcnt vmcnt(" #n ")" ::: "memory")
; #define PG8_BAR __builtin_amdgcn_s_barrier()
; template <class Epi, class Sched, bool ALIGN_EPI = false, bool SP2 = false>
; __device__ __forceinline__ void gemm_phase(PG8_LAS unsigned char* lds, const Gemm g, const Sched& S, const Epi& E) {
;     ...
;     const int K = g.K, nt = K / BK;
;     unsigned voffA[2], voffB[2];
; #pragma unroll
;     for (int i = 0; i < 2; ++i) { int R, C; stage_rc(tid * 16 + i * 8192, R, C); const int Rb = Epi::PERM ? ((R & ~31) + perm32(R & 31)) : R;
;         voffA[i] = (unsigned)(R * K + C) * 2u; voffB[i] = (unsigned)(Rb * K + C) * 2u; }
;     const size_t kstep = (size_t)(BK * 2);
;     const size_t hstep = (size_t)HALF * K * 2;
;     const size_t tstep = 2 * hstep;
;     const unsigned ldsw = (unsigned)wid * 1024u;
;     const int aoff = lds_byte(wr * 64 + fr, fq * 8), boff = lds_byte(wc * 32 + fr, fq * 8);
;     ...
;         PG8_WAIT_V(2); PG8_BAR;
;         PG8_STAGE(PG8_SB(1, 0), cB + kstep, voffB); PG8_STAGE(PG8_SA(1, 0), cA + kstep, voffA); PG8_STAGE(PG8_SB(1, 1), cB + hstep + kstep, voffB);
;         PG8_WAIT_V(6); PG8_BAR;
.LBB0_686:
	s_and_b64 s[24:25], s[30:31], exec
	v_readlane_b32 s24, v255, 35
	v_readlane_b32 s25, v255, 36
	v_readlane_b32 s19, v255, 34
	s_cselect_b32 s31, s25, s57
	s_cselect_b32 s30, s24, s56
	s_cselect_b32 s94, s23, s19
	s_cselect_b32 s95, s65, s68
	s_add_i32 m0, s90, 0x18000
	v_lshl_add_u64 v[0:1], v[0:1], 0, s[14:15]
	s_waitcnt vmcnt(2)
	s_barrier
	global_load_lds_dwordx4 v[0:1], off
	v_lshl_add_u64 v[0:1], v[2:3], 0, s[14:15]
	s_add_i32 m0, s90, 0x1a000
	s_add_i32 s96, s90, 0x8000
	global_load_lds_dwordx4 v[0:1], off
	v_lshl_add_u64 v[0:1], v[8:9], 0, s[14:15]
	s_mov_b32 m0, s96
	s_add_i32 s97, s90, 0xa000
	global_load_lds_dwordx4 v[0:1], off
	v_lshl_add_u64 v[0:1], v[10:11], 0, s[14:15]
	s_mov_b32 m0, s97
	s_lshl_b32 s22, s22, 5
	global_load_lds_dwordx4 v[0:1], off
	s_add_i32 m0, s90, 0x1c000
	v_lshl_add_u64 v[0:1], v[4:5], 0, s[14:15]
	global_load_lds_dwordx4 v[0:1], off
	v_lshl_add_u64 v[0:1], v[6:7], 0, s[14:15]
	s_add_i32 m0, s90, 0x1e000
	s_and_b32 s51, s22, 0x60
	global_load_lds_dwordx4 v[0:1], off
	s_lshr_b32 s78, s7, 6
	s_lshl_b32 s50, s33, 6
	s_lshl_b32 s24, s33, 13
	s_lshl_b32 s22, s51, 7
	v_lshrrev_b32_e32 v0, 1, v12
	s_cmp_lg_u32 s7, 0
	v_and_b32_e32 v145, 24, v0
	s_cselect_b64 s[34:35], -1, 0
	s_add_i32 s79, s78, -2
	v_and_b32_e32 v144, 15, v12
	v_lshlrev_b32_e32 v1, 1, v145
	v_lshlrev_b32_e32 v2, 2, v12
	s_cmpk_lt_u32 s1, 0x100
	v_lshl_or_b32 v1, v144, 6, v1
	v_and_b32_e32 v2, 32, v2
	s_cselect_b64 s[36:37], -1, 0
	s_lshr_b32 s82, s0, 5
	v_bitop3_b32 v3, v1, s24, v2 bitop3:0xde
	v_bitop3_b32 v147, v1, s22, v2 bitop3:0xde
	v_lshlrev_b32_e32 v1, 1, v12
	v_and_b32_e32 v0, 4, v0
	s_abs_i32 s44, s82
	v_and_or_b32 v149, v1, 8, v0
	v_cvt_f32_u32_e32 v0, s44
	s_sub_i32 s1, 0, s44
	s_waitcnt vmcnt(0)
	s_lshr_b32 s45, s6, 3
	v_rcp_iflag_f32_e32 v0, v0
	s_mov_b32 s33, 0
	v_or_b32_e32 v146, 16, v144
	v_and_or_b32 v151, v12, 3, v149
	v_mul_f32_e32 v0, 0x4f7ffffe, v0
	v_cvt_u32_f32_e32 v0, v0
	v_or_b32_e32 v148, 0x80, v144
	v_or_b32_e32 v150, 0x90, v144
	s_mov_b32 s7, s11
	v_readfirstlane_b32 s24, v0
	v_add_u32_e32 v0, v15, v13
	s_mul_i32 s1, s1, s24
	v_add_lshl_u32 v132, v0, v14, 1
	v_add_u32_e32 v0, v18, v16
	s_mul_hi_u32 s1, s24, s1
	v_lshl_add_u64 v[152:153], s[10:11], 0, v[132:133]
	v_add_lshl_u32 v132, v0, v17, 1
	s_and_b32 s74, s6, 4
	s_add_i32 s22, s45, 1
	s_ashr_i32 s0, s82, 31
	s_add_i32 s1, s24, s1
	v_lshl_add_u64 v[154:155], s[10:11], 0, v[132:133]
	v_add_u32_e32 v160, 0, v3
	s_barrier
	s_branch .LBB0_689

; #define PG8_STAGE(bufoff, gbase, voff) do { _Pragma("unroll") for (int _i = 0; _i < 2; ++_i) \
;         __builtin_amdgcn_global_load_lds((const unsigned*)((const char*)(gbase) + (voff)[_i]), (PG8_LAS unsigned*)(lds + (bufoff) + ldsw + _i * 8192), 16, 0, 0); } while (0)
; #define PG8_LDA(dst, b, h) do { _Pragma("unroll") for (int m = 0; m < 4; ++m) _Pragma("unroll") for (int k = 0; k < 2; ++k) dst[m][k] = *(const PG8_LAS bf16x8*)(lds + PG8_SA(b, h) + aoff + m * 2048 + k * 1024); } while (0)
; #define PG8_LDB(dst, b, h) do { _Pragma("unroll") for (int n = 0; n < 2; ++n) _Pragma("unroll") for (int k = 0; k < 2; ++k) dst[n][k] = *(const PG8_LAS bf16x8*)(lds + PG8_SB(b, h) + boff + n * 2048 + k * 1024); } while (0)
; #define PG8_WAIT_V(n) asm volatile("s_waitcnt vmcnt(" #n ")" ::: "memory")
; #define PG8_WAIT_L(n) asm volatile("s_waitcnt lgkmcnt(" #n ")" ::: "memory")
; #define PG8_BAR __builtin_amdgcn_s_barrier()
; #define PG8_SCHED __builtin_amdgcn_sched_barrier(0)
; template <class Epi, class Sched, bool ALIGN_EPI = false, bool SP2 = false>
; __device__ __forceinline__ void gemm_phase(PG8_LAS unsigned char* lds, const Gemm g, const Sched& S, const Epi& E) {
;     ...
;         const char* nA = has_next ? (const char*)g.A + (size_t)nxt.pm * tstep : cA; const char* nB = has_next ? (const char*)g.Bt + (size_t)nxt.pn * tstep : cB;
;         for (int t = 0; t < nt; t += 2) {
;             const bool last = (t == nt - 2);
;             const char* a1 = cA + (size_t)(t + 1) * kstep;
;             const char* a2 = last ? nA : cA + (size_t)(t + 2) * kstep; const char* b2 = last ? nB : cB + (size_t)(t + 2) * kstep;
;             const char* a3 = a2 + kstep; const char* b3 = b2 + kstep;
;             if (last && has_next) S.a_ready(nxt);
;             if constexpr (SP2) {
;             PG8_LDB(B0, 0, 0); PG8_LDB(B1, 0, 1); PG8_SCHED; PG8_LDA(At, 0, 0); PG8_STAGE(PG8_SA(1, 1), a1 + hstep, voffA);
;             PG8_WAIT_V(8); PG8_WAIT_L(0); PG8_BAR; PG8_MMA(0, 0, At, B0); PG8_MMA(0, 1, At, B1); PG8_BAR; PG8_SCHED;
;             PG8_LDA(At, 0, 1); PG8_STAGE(PG8_SB(0, 0), b2, voffB); PG8_STAGE(PG8_SB(0, 1), b2 + hstep, voffB); PG8_STAGE(PG8_SA(0, 0), a2, voffA);
;             PG8_WAIT_V(8); PG8_WAIT_L(0); PG8_BAR; PG8_MMA(1, 0, At, B0); PG8_MMA(1, 1, At, B1); PG8_BAR; PG8_SCHED;
.LBB0_698:
	s_add_u32 s48, s48, 0x80
	s_addc_u32 s49, s49, 0
	s_add_u32 s59, s52, 0x100
	s_addc_u32 vcc_lo, s53, 0
	s_mov_b32 s52, 0
	s_add_i32 vcc_hi, s52, 2
	s_add_u32 s24, s48, 0x80
	s_addc_u32 s25, s49, 0
	s_add_i32 s66, 0, 0x10000
	s_cmp_eq_u32 s79, s52
	s_cselect_b32 s53, s39, s25
	s_cselect_b32 s52, s38, s24
	v_add_u32_e32 v132, s66, v147
	s_cselect_b32 s25, s43, vcc_lo
	s_cselect_b32 s24, s42, s59
	s_add_i32 s29, 0, 0x14000
	ds_read_b128 v[156:159], v132
	ds_read_b128 v[162:165], v132 offset:1024
	ds_read_b128 v[166:169], v132 offset:2048
	ds_read_b128 v[192:195], v132 offset:3072
	v_add_u32_e32 v132, s29, v147
	ds_read_b128 v[196:199], v132
	ds_read_b128 v[200:203], v132 offset:1024
	ds_read_b128 v[204:207], v132 offset:2048
	ds_read_b128 v[208:211], v132 offset:3072
	v_lshl_add_u64 v[170:171], s[48:49], 0, v[152:153]
	s_add_i32 m0, s90, 0xc000
	ds_read_b128 v[212:215], v160
	ds_read_b128 v[216:219], v160 offset:1024
	ds_read_b128 v[220:223], v160 offset:2048
	ds_read_b128 v[224:227], v160 offset:3072
	ds_read_b128 v[228:231], v160 offset:4096
	ds_read_b128 v[232:235], v160 offset:5120
	ds_read_b128 v[236:239], v160 offset:6144
	ds_read_b128 v[240:243], v160 offset:7168
	global_load_lds_dwordx4 v[170:171], off
	v_lshl_add_u64 v[170:171], s[48:49], 0, v[154:155]
	s_add_i32 m0, s90, 0xe000
	s_nop 0
	global_load_lds_dwordx4 v[170:171], off
	s_waitcnt vmcnt(24)
	s_waitcnt lgkmcnt(0)
	s_barrier
	s_setprio 1
	s_waitcnt lgkmcnt(0)
	v_mfma_f32_16x16x32_bf16 v[124:127], v[156:159], v[212:215], 0
	v_mfma_f32_16x16x32_bf16 v[120:123], v[166:169], v[212:215], 0
	v_mfma_f32_16x16x32_bf16 v[108:111], v[156:159], v[220:223], 0
	v_mfma_f32_16x16x32_bf16 v[104:107], v[166:169], v[220:223], 0
	v_mfma_f32_16x16x32_bf16 v[92:95], v[156:159], v[228:231], 0
	v_mfma_f32_16x16x32_bf16 v[88:91], v[166:169], v[228:231], 0
	v_mfma_f32_16x16x32_bf16 v[76:79], v[156:159], v[236:239], 0
	v_mfma_f32_16x16x32_bf16 v[72:75], v[166:169], v[236:239], 0
	v_mfma_f32_16x16x32_bf16 v[124:127], v[162:165], v[216:219], v[124:127]
	v_mfma_f32_16x16x32_bf16 v[120:123], v[192:195], v[216:219], v[120:123]
	v_mfma_f32_16x16x32_bf16 v[108:111], v[162:165], v[224:227], v[108:111]
	v_mfma_f32_16x16x32_bf16 v[104:107], v[192:195], v[224:227], v[104:107]
	v_mfma_f32_16x16x32_bf16 v[92:95], v[162:165], v[232:235], v[92:95]
	v_mfma_f32_16x16x32_bf16 v[88:91], v[192:195], v[232:235], v[88:91]
	v_mfma_f32_16x16x32_bf16 v[76:79], v[162:165], v[240:243], v[76:79]
	v_mfma_f32_16x16x32_bf16 v[72:75], v[192:195], v[240:243], v[72:75]
	s_setprio 0
	s_setprio 1
	v_mfma_f32_16x16x32_bf16 v[116:119], v[196:199], v[212:215], 0
	v_mfma_f32_16x16x32_bf16 v[112:115], v[204:207], v[212:215], 0
	v_mfma_f32_16x16x32_bf16 v[100:103], v[196:199], v[220:223], 0
	v_mfma_f32_16x16x32_bf16 v[96:99], v[204:207], v[220:223], 0
	v_mfma_f32_16x16x32_bf16 v[84:87], v[196:199], v[228:231], 0
	v_mfma_f32_16x16x32_bf16 v[80:83], v[204:207], v[228:231], 0
	v_mfma_f32_16x16x32_bf16 v[68:71], v[196:199], v[236:239], 0
	v_mfma_f32_16x16x32_bf16 v[64:67], v[204:207], v[236:239], 0
	v_mfma_f32_16x16x32_bf16 v[116:119], v[200:203], v[216:219], v[116:119]
	v_mfma_f32_16x16x32_bf16 v[112:115], v[208:211], v[216:219], v[112:115]
	v_mfma_f32_16x16x32_bf16 v[100:103], v[200:203], v[224:227], v[100:103]
	v_mfma_f32_16x16x32_bf16 v[96:99], v[208:211], v[224:227], v[96:99]
	v_mfma_f32_16x16x32_bf16 v[84:87], v[200:203], v[232:235], v[84:87]
	v_mfma_f32_16x16x32_bf16 v[80:83], v[208:211], v[232:235], v[80:83]
	v_mfma_f32_16x16x32_bf16 v[68:71], v[200:203], v[240:243], v[68:71]
	v_mfma_f32_16x16x32_bf16 v[64:67], v[208:211], v[240:243], v[64:67]
	s_setprio 0
	s_barrier
	s_add_i32 s66, s66, s89
	v_lshl_add_u64 v[170:171], s[24:25], 0, v[130:131]
	s_mov_b32 m0, s66
	ds_read_b128 v[212:215], v160 offset:16384
	ds_read_b128 v[216:219], v160 offset:17408
	ds_read_b128 v[220:223], v160 offset:18432
	ds_read_b128 v[224:227], v160 offset:19456
	ds_read_b128 v[228:231], v160 offset:20480
	ds_read_b128 v[232:235], v160 offset:21504
	ds_read_b128 v[236:239], v160 offset:22528
	ds_read_b128 v[240:243], v160 offset:23552
	global_load_lds_dwordx4 v[170:171], off
	s_add_i32 m0, s66, 0x2000
	v_lshl_add_u64 v[244:245], s[24:25], 0, v[142:143]
	s_add_u32 s24, s24, s10
	s_addc_u32 s25, s25, 0
	s_add_i32 s29, s29, s89
	global_load_lds_dwordx4 v[244:245], off
	v_lshl_add_u64 v[246:247], s[24:25], 0, v[130:131]
	s_mov_b32 m0, s29
	v_lshl_add_u64 v[248:249], s[24:25], 0, v[142:143]
	global_load_lds_dwordx4 v[246:247], off
	s_add_i32 m0, s29, 0x2000
	v_lshl_add_u64 v[250:251], s[52:53], 0, v[128:129]
	global_load_lds_dwordx4 v[248:249], off
	s_mov_b32 m0, s90
	v_lshl_add_u64 v[252:253], s[52:53], 0, v[140:141]
	global_load_lds_dwordx4 v[250:251], off
	s_mov_b32 m0, s91
	s_nop 0
	global_load_lds_dwordx4 v[252:253], off
	s_waitcnt vmcnt(24)
	s_waitcnt lgkmcnt(0)
	s_barrier
; #define PG8_STAGE(bufoff, gbase, voff) do { _Pragma("unroll") for (int _i = 0; _i < 2; ++_i) \
;         __builtin_amdgcn_global_load_lds((const unsigned*)((const char*)(gbase) + (voff)[_i]), (PG8_LAS unsigned*)(lds + (bufoff) + ldsw + _i * 8192), 16, 0, 0); } while (0)
; #define PG8_LDA(dst, b, h) do { _Pragma("unroll") for (int m = 0; m < 4; ++m) _Pragma("unroll") for (int k = 0; k < 2; ++k) dst[m][k] = *(const PG8_LAS bf16x8*)(lds + PG8_SA(b, h) + aoff + m * 2048 + k * 1024); } while (0)
; #define PG8_LDB(dst, b, h) do { _Pragma("unroll") for (int n = 0; n < 2; ++n) _Pragma("unroll") for (int k = 0; k < 2; ++k) dst[n][k] = *(const PG8_LAS bf16x8*)(lds + PG8_SB(b, h) + boff + n * 2048 + k * 1024); } while (0)
; #define PG8_MMA(ai, bj, At, Bt) do { __builtin_amdgcn_s_setprio(1); _Pragma("unroll") for (int m = 0; m < 4; ++m) _Pragma("unroll") for (int n = 0; n < 2; ++n) _Pragma("unroll") for (int k = 0; k < 2; ++k) \
;         acc[ai][bj][m][n] = __builtin_amdgcn_mfma_f32_16x16x32_bf16(Bt[n][k], At[m][k], acc[ai][bj][m][n], 0, 0, 0); __builtin_amdgcn_s_setprio(0); } while (0)
; #define PG8_WAIT_V(n) asm volatile("s_waitcnt vmcnt(" #n ")" ::: "memory")
; #define PG8_WAIT_L(n) asm volatile("s_waitcnt lgkmcnt(" #n ")" ::: "memory")
; #define PG8_BAR __builtin_amdgcn_s_barrier()
; #define PG8_SCHED __builtin_amdgcn_sched_barrier(0)
; template <class Epi, class Sched, bool ALIGN_EPI = false, bool SP2 = false>
; __device__ __forceinline__ void gemm_phase(PG8_LAS unsigned char* lds, const Gemm g, const Sched& S, const Epi& E) {
;     ...
;             PG8_WAIT_V(8); PG8_WAIT_L(0); PG8_BAR; PG8_MMA(1, 0, At, B0); PG8_MMA(1, 1, At, B1); PG8_BAR; PG8_SCHED;
;             PG8_LDB(B0, 1, 0); PG8_LDB(B1, 1, 1); PG8_SCHED; PG8_LDA(At, 1, 0); PG8_STAGE(PG8_SA(0, 1), a2 + hstep, voffA);
;             PG8_WAIT_V(8); PG8_WAIT_L(0); PG8_BAR; PG8_MMA(0, 0, At, B0); PG8_MMA(0, 1, At, B1); PG8_BAR; PG8_SCHED;
	s_setprio 1
	s_waitcnt lgkmcnt(0)
	v_mfma_f32_16x16x32_bf16 v[60:63], v[156:159], v[212:215], 0
	v_mfma_f32_16x16x32_bf16 v[56:59], v[166:169], v[212:215], 0
	v_mfma_f32_16x16x32_bf16 v[44:47], v[156:159], v[220:223], 0
	v_mfma_f32_16x16x32_bf16 v[40:43], v[166:169], v[220:223], 0
	v_mfma_f32_16x16x32_bf16 v[28:31], v[156:159], v[228:231], 0
	v_mfma_f32_16x16x32_bf16 v[24:27], v[166:169], v[228:231], 0
	v_mfma_f32_16x16x32_bf16 v[12:15], v[156:159], v[236:239], 0
	v_mfma_f32_16x16x32_bf16 v[8:11], v[166:169], v[236:239], 0
	v_mfma_f32_16x16x32_bf16 v[60:63], v[162:165], v[216:219], v[60:63]
	v_mfma_f32_16x16x32_bf16 v[56:59], v[192:195], v[216:219], v[56:59]
	v_mfma_f32_16x16x32_bf16 v[44:47], v[162:165], v[224:227], v[44:47]
	v_mfma_f32_16x16x32_bf16 v[40:43], v[192:195], v[224:227], v[40:43]
	v_mfma_f32_16x16x32_bf16 v[28:31], v[162:165], v[232:235], v[28:31]
	v_mfma_f32_16x16x32_bf16 v[24:27], v[192:195], v[232:235], v[24:27]
	v_mfma_f32_16x16x32_bf16 v[12:15], v[162:165], v[240:243], v[12:15]
	v_mfma_f32_16x16x32_bf16 v[8:11], v[192:195], v[240:243], v[8:11]
	s_setprio 0
	s_setprio 1
	v_mfma_f32_16x16x32_bf16 v[52:55], v[196:199], v[212:215], 0
	v_mfma_f32_16x16x32_bf16 v[48:51], v[204:207], v[212:215], 0
	v_mfma_f32_16x16x32_bf16 v[36:39], v[196:199], v[220:223], 0
	v_mfma_f32_16x16x32_bf16 v[32:35], v[204:207], v[220:223], 0
	v_mfma_f32_16x16x32_bf16 v[20:23], v[196:199], v[228:231], 0
	v_mfma_f32_16x16x32_bf16 v[16:19], v[204:207], v[228:231], 0
	v_mfma_f32_16x16x32_bf16 v[4:7], v[196:199], v[236:239], 0
	v_mfma_f32_16x16x32_bf16 v[0:3], v[204:207], v[236:239], 0
	v_mfma_f32_16x16x32_bf16 v[52:55], v[200:203], v[216:219], v[52:55]
	v_mfma_f32_16x16x32_bf16 v[48:51], v[208:211], v[216:219], v[48:51]
	v_mfma_f32_16x16x32_bf16 v[36:39], v[200:203], v[224:227], v[36:39]
	v_mfma_f32_16x16x32_bf16 v[32:35], v[208:211], v[224:227], v[32:35]
	v_mfma_f32_16x16x32_bf16 v[20:23], v[200:203], v[232:235], v[20:23]
	v_mfma_f32_16x16x32_bf16 v[16:19], v[208:211], v[232:235], v[16:19]
	v_mfma_f32_16x16x32_bf16 v[4:7], v[200:203], v[240:243], v[4:7]
	v_mfma_f32_16x16x32_bf16 v[0:3], v[208:211], v[240:243], v[0:3]
	s_setprio 0
	s_barrier
	s_add_i32 s29, 0, 0x18000
	v_add_u32_e32 v132, s29, v147
	s_add_i32 s66, 0, 0x1c000
	ds_read_b128 v[156:159], v132
	ds_read_b128 v[162:165], v132 offset:1024
	ds_read_b128 v[166:169], v132 offset:2048
	ds_read_b128 v[192:195], v132 offset:3072
	v_add_u32_e32 v132, s66, v147
	ds_read_b128 v[196:199], v132
	ds_read_b128 v[200:203], v132 offset:1024
	ds_read_b128 v[204:207], v132 offset:2048
	ds_read_b128 v[208:211], v132 offset:3072
	s_add_u32 s24, s52, s10
	s_addc_u32 s25, s53, 0
	s_mov_b32 m0, s92
	v_lshl_add_u64 v[184:185], s[24:25], 0, v[128:129]
	ds_read_b128 v[212:215], v160 offset:32768
	ds_read_b128 v[216:219], v160 offset:33792
	ds_read_b128 v[220:223], v160 offset:34816
	ds_read_b128 v[224:227], v160 offset:35840
	ds_read_b128 v[228:231], v160 offset:36864
	ds_read_b128 v[232:235], v160 offset:37888
	ds_read_b128 v[236:239], v160 offset:38912
	ds_read_b128 v[240:243], v160 offset:39936
	global_load_lds_dwordx4 v[184:185], off
	v_lshl_add_u64 v[184:185], s[24:25], 0, v[140:141]
	s_mov_b32 m0, s93
	s_nop 0
	global_load_lds_dwordx4 v[184:185], off
	s_waitcnt vmcnt(8)
	s_waitcnt lgkmcnt(0)
	s_barrier
	s_setprio 1
	s_waitcnt lgkmcnt(0)
	v_mfma_f32_16x16x32_bf16 v[124:127], v[156:159], v[212:215], v[124:127]
	v_mfma_f32_16x16x32_bf16 v[120:123], v[166:169], v[212:215], v[120:123]
	v_mfma_f32_16x16x32_bf16 v[108:111], v[156:159], v[220:223], v[108:111]
	v_mfma_f32_16x16x32_bf16 v[104:107], v[166:169], v[220:223], v[104:107]
	v_mfma_f32_16x16x32_bf16 v[92:95], v[156:159], v[228:231], v[92:95]
	v_mfma_f32_16x16x32_bf16 v[88:91], v[166:169], v[228:231], v[88:91]
	v_mfma_f32_16x16x32_bf16 v[76:79], v[156:159], v[236:239], v[76:79]
	v_mfma_f32_16x16x32_bf16 v[72:75], v[166:169], v[236:239], v[72:75]
	v_mfma_f32_16x16x32_bf16 v[124:127], v[162:165], v[216:219], v[124:127]
	v_mfma_f32_16x16x32_bf16 v[120:123], v[192:195], v[216:219], v[120:123]
	v_mfma_f32_16x16x32_bf16 v[108:111], v[162:165], v[224:227], v[108:111]
	v_mfma_f32_16x16x32_bf16 v[104:107], v[192:195], v[224:227], v[104:107]
	v_mfma_f32_16x16x32_bf16 v[92:95], v[162:165], v[232:235], v[92:95]
	v_mfma_f32_16x16x32_bf16 v[88:91], v[192:195], v[232:235], v[88:91]
	v_mfma_f32_16x16x32_bf16 v[76:79], v[162:165], v[240:243], v[76:79]
	v_mfma_f32_16x16x32_bf16 v[72:75], v[192:195], v[240:243], v[72:75]
	s_setprio 0
	s_setprio 1
	v_mfma_f32_16x16x32_bf16 v[116:119], v[196:199], v[212:215], v[116:119]
	v_mfma_f32_16x16x32_bf16 v[112:115], v[204:207], v[212:215], v[112:115]
	v_mfma_f32_16x16x32_bf16 v[100:103], v[196:199], v[220:223], v[100:103]
	v_mfma_f32_16x16x32_bf16 v[96:99], v[204:207], v[220:223], v[96:99]
	v_mfma_f32_16x16x32_bf16 v[84:87], v[196:199], v[228:231], v[84:87]
	v_mfma_f32_16x16x32_bf16 v[80:83], v[204:207], v[228:231], v[80:83]
	v_mfma_f32_16x16x32_bf16 v[68:71], v[196:199], v[236:239], v[68:71]
	v_mfma_f32_16x16x32_bf16 v[64:67], v[204:207], v[236:239], v[64:67]
	v_mfma_f32_16x16x32_bf16 v[116:119], v[200:203], v[216:219], v[116:119]
	v_mfma_f32_16x16x32_bf16 v[112:115], v[208:211], v[216:219], v[112:115]
	v_mfma_f32_16x16x32_bf16 v[100:103], v[200:203], v[224:227], v[100:103]
	v_mfma_f32_16x16x32_bf16 v[96:99], v[208:211], v[224:227], v[96:99]
	v_mfma_f32_16x16x32_bf16 v[84:87], v[200:203], v[232:235], v[84:87]
	v_mfma_f32_16x16x32_bf16 v[80:83], v[208:211], v[232:235], v[80:83]
	v_mfma_f32_16x16x32_bf16 v[68:71], v[200:203], v[240:243], v[68:71]
	v_mfma_f32_16x16x32_bf16 v[64:67], v[208:211], v[240:243], v[64:67]
	s_setprio 0
	s_barrier
; #define PG8_STAGE(bufoff, gbase, voff) do { _Pragma("unroll") for (int _i = 0; _i < 2; ++_i) \
;         __builtin_amdgcn_global_load_lds((const unsigned*)((const char*)(gbase) + (voff)[_i]), (PG8_LAS unsigned*)(lds + (bufoff) + ldsw + _i * 8192), 16, 0, 0); } while (0)
; #define PG8_LDA(dst, b, h) do { _Pragma("unroll") for (int m = 0; m < 4; ++m) _Pragma("unroll") for (int k = 0; k < 2; ++k) dst[m][k] = *(const PG8_LAS bf16x8*)(lds + PG8_SA(b, h) + aoff + m * 2048 + k * 1024); } while (0)
; #define PG8_MMA(ai, bj, At, Bt) do { __builtin_amdgcn_s_setprio(1); _Pragma("unroll") for (int m = 0; m < 4; ++m) _Pragma("unroll") for (int n = 0; n < 2; ++n) _Pragma("unroll") for (int k = 0; k < 2; ++k) \
;         acc[ai][bj][m][n] = __builtin_amdgcn_mfma_f32_16x16x32_bf16(Bt[n][k], At[m][k], acc[ai][bj][m][n], 0, 0, 0); __builtin_amdgcn_s_setprio(0); } while (0)
; #define PG8_WAIT_V(n) asm volatile("s_waitcnt vmcnt(" #n ")" ::: "memory")
; #define PG8_WAIT_L(n) asm volatile("s_waitcnt lgkmcnt(" #n ")" ::: "memory")
; #define PG8_BAR __builtin_amdgcn_s_barrier()
; #define PG8_SCHED __builtin_amdgcn_sched_barrier(0)
; template <class Epi, class Sched, bool ALIGN_EPI = false, bool SP2 = false>
; __device__ __forceinline__ void gemm_phase(PG8_LAS unsigned char* lds, const Gemm g, const Sched& S, const Epi& E) {
;     ...
;         for (int t = 0; t < nt; t += 2) {
;     ...
;             PG8_LDA(At, 1, 1); PG8_STAGE(PG8_SB(1, 0), b3, voffB); PG8_STAGE(PG8_SB(1, 1), b3 + hstep, voffB); PG8_STAGE(PG8_SA(1, 0), a3, voffA);
;             PG8_WAIT_V(8); PG8_WAIT_L(0); PG8_BAR; PG8_MMA(1, 0, At, B0); PG8_MMA(1, 1, At, B1); PG8_BAR; PG8_SCHED;
	s_add_i32 s24, s29, s89
	v_lshl_add_u64 v[170:171], v[170:171], 0, s[14:15]
	s_mov_b32 m0, s24
	ds_read_b128 v[212:215], v160 offset:49152
	ds_read_b128 v[216:219], v160 offset:50176
	ds_read_b128 v[220:223], v160 offset:51200
	ds_read_b128 v[224:227], v160 offset:52224
	ds_read_b128 v[228:231], v160 offset:53248
	ds_read_b128 v[232:235], v160 offset:54272
	ds_read_b128 v[236:239], v160 offset:55296
	ds_read_b128 v[240:243], v160 offset:56320
	global_load_lds_dwordx4 v[170:171], off
	v_lshl_add_u64 v[170:171], v[244:245], 0, s[14:15]
	s_add_i32 m0, s24, 0x2000
	s_add_i32 s24, s66, s89
	global_load_lds_dwordx4 v[170:171], off
	v_lshl_add_u64 v[170:171], v[246:247], 0, s[14:15]
	s_mov_b32 m0, s24
	s_nop 0
	global_load_lds_dwordx4 v[170:171], off
	v_lshl_add_u64 v[170:171], v[248:249], 0, s[14:15]
	s_add_i32 m0, s24, 0x2000
	s_nop 0
	global_load_lds_dwordx4 v[170:171], off
	v_lshl_add_u64 v[170:171], v[250:251], 0, s[14:15]
	s_mov_b32 m0, s96
	s_nop 0
	global_load_lds_dwordx4 v[170:171], off
	v_lshl_add_u64 v[170:171], v[252:253], 0, s[14:15]
	s_mov_b32 m0, s97
	s_nop 0
	global_load_lds_dwordx4 v[170:171], off
	s_waitcnt vmcnt(8)
	s_waitcnt lgkmcnt(0)
	s_barrier
	s_setprio 1
	s_waitcnt lgkmcnt(0)
	v_mfma_f32_16x16x32_bf16 v[60:63], v[156:159], v[212:215], v[60:63]
	v_mfma_f32_16x16x32_bf16 v[56:59], v[166:169], v[212:215], v[56:59]
	v_mfma_f32_16x16x32_bf16 v[44:47], v[156:159], v[220:223], v[44:47]
	v_mfma_f32_16x16x32_bf16 v[40:43], v[166:169], v[220:223], v[40:43]
	v_mfma_f32_16x16x32_bf16 v[28:31], v[156:159], v[228:231], v[28:31]
	v_mfma_f32_16x16x32_bf16 v[24:27], v[166:169], v[228:231], v[24:27]
	v_mfma_f32_16x16x32_bf16 v[12:15], v[156:159], v[236:239], v[12:15]
	v_mfma_f32_16x16x32_bf16 v[8:11], v[166:169], v[236:239], v[8:11]
	v_mfma_f32_16x16x32_bf16 v[60:63], v[162:165], v[216:219], v[60:63]
	v_mfma_f32_16x16x32_bf16 v[56:59], v[192:195], v[216:219], v[56:59]
	v_mfma_f32_16x16x32_bf16 v[44:47], v[162:165], v[224:227], v[44:47]
	v_mfma_f32_16x16x32_bf16 v[40:43], v[192:195], v[224:227], v[40:43]
	v_mfma_f32_16x16x32_bf16 v[28:31], v[162:165], v[232:235], v[28:31]
	v_mfma_f32_16x16x32_bf16 v[24:27], v[192:195], v[232:235], v[24:27]
	v_mfma_f32_16x16x32_bf16 v[12:15], v[162:165], v[240:243], v[12:15]
	v_mfma_f32_16x16x32_bf16 v[8:11], v[192:195], v[240:243], v[8:11]
	s_setprio 0
	s_setprio 1
	v_mfma_f32_16x16x32_bf16 v[52:55], v[196:199], v[212:215], v[52:55]
	v_mfma_f32_16x16x32_bf16 v[48:51], v[204:207], v[212:215], v[48:51]
	v_mfma_f32_16x16x32_bf16 v[36:39], v[196:199], v[220:223], v[36:39]
	v_mfma_f32_16x16x32_bf16 v[32:35], v[204:207], v[220:223], v[32:35]
	v_mfma_f32_16x16x32_bf16 v[20:23], v[196:199], v[228:231], v[20:23]
	v_mfma_f32_16x16x32_bf16 v[16:19], v[204:207], v[228:231], v[16:19]
	v_mfma_f32_16x16x32_bf16 v[4:7], v[196:199], v[236:239], v[4:7]
	v_mfma_f32_16x16x32_bf16 v[0:3], v[204:207], v[236:239], v[0:3]
	v_mfma_f32_16x16x32_bf16 v[52:55], v[200:203], v[216:219], v[52:55]
	v_mfma_f32_16x16x32_bf16 v[48:51], v[208:211], v[216:219], v[48:51]
	v_mfma_f32_16x16x32_bf16 v[36:39], v[200:203], v[224:227], v[36:39]
	v_mfma_f32_16x16x32_bf16 v[32:35], v[208:211], v[224:227], v[32:35]
	v_mfma_f32_16x16x32_bf16 v[20:23], v[200:203], v[232:235], v[20:23]
	v_mfma_f32_16x16x32_bf16 v[16:19], v[208:211], v[232:235], v[16:19]
	v_mfma_f32_16x16x32_bf16 v[4:7], v[200:203], v[240:243], v[4:7]
	v_mfma_f32_16x16x32_bf16 v[0:3], v[208:211], v[240:243], v[0:3]
	s_setprio 0
	s_barrier
	s_add_u32 s48, s48, 0x100
	s_addc_u32 s49, s49, 0
	s_add_u32 s59, s59, 0x100
	s_addc_u32 vcc_lo, vcc_lo, 0
	s_cmp_ge_u32 vcc_hi, s78
	s_mov_b32 s52, vcc_hi
